# mixer pooling matmul: all first-half fragments requested before the scan, single covering wait after it; on top of per-class in-proj epilogues
# speedup vs baseline: 1.0414x; 1.0073x over previous
.LBB0_776:
	s_or_b64 exec, exec, s[0:1]
	s_waitcnt vmcnt(0)
	v_ashrrev_i32_e32 v0, 7, v136
	v_lshlrev_b32_e64 v0, v0, 2
	v_cmp_gt_i32_e32 vcc, 2, v0
	v_lshlrev_b32_e32 v1, 1, v136
	s_waitcnt lgkmcnt(0)
	s_barrier
	s_lshl_b32 s32, s27, 17
	s_add_u32 s32, s10, s32
	s_addc_u32 s33, s11, 0
	s_add_u32 s32, s32, 0x3800000
	s_addc_u32 s33, s33, 0
	v_lshrrev_b32_e32 v137, 7, v136
	v_and_b32_e32 v138, 15, v136
	v_bfe_u32 v139, v136, 4, 2
	v_lshlrev_b32_e32 v140, 15, v137
	v_lshl_or_b32 v140, v138, 8, v140
	v_lshl_or_b32 v140, v139, 4, v140
	v_add_u32_e32 v144, 0x1000, v140
	v_add_u32_e32 v145, 0x2000, v140
	v_add_u32_e32 v146, 0x3000, v140
	global_load_dwordx4 v[108:111], v140, s[32:33]
	global_load_dwordx4 v[104:107], v140, s[32:33] offset:64
	global_load_dwordx4 v[100:103], v140, s[32:33] offset:128
	global_load_dwordx4 v[96:99], v140, s[32:33] offset:192
	global_load_dwordx4 v[88:91], v144, s[32:33]
	global_load_dwordx4 v[84:87], v144, s[32:33] offset:64
	global_load_dwordx4 v[80:83], v144, s[32:33] offset:128
	global_load_dwordx4 v[76:79], v144, s[32:33] offset:192
	global_load_dwordx4 v[68:71], v145, s[32:33]
	global_load_dwordx4 v[64:67], v145, s[32:33] offset:64
	global_load_dwordx4 v[60:63], v145, s[32:33] offset:128
	global_load_dwordx4 v[56:59], v145, s[32:33] offset:192
	global_load_dwordx4 v[48:51], v146, s[32:33]
	global_load_dwordx4 v[44:47], v146, s[32:33] offset:64
	global_load_dwordx4 v[40:43], v146, s[32:33] offset:128
	global_load_dwordx4 v[36:39], v146, s[32:33] offset:192
	v_lshlrev_b32_e32 v141, 9, v137
	v_lshl_or_b32 v141, v139, 4, v141
	global_load_dwordx4 v[92:95], v141, s[66:67]
	global_load_dwordx4 v[72:75], v141, s[66:67] offset:64
	global_load_dwordx4 v[52:55], v141, s[66:67] offset:128
	global_load_dwordx4 v[148:151], v141, s[66:67] offset:192
	s_lshl_b32 s34, s38, 11
	s_add_u32 s34, s10, s34
	s_addc_u32 s35, s11, 0
	s_add_u32 s34, s34, 0x1c801000
	s_addc_u32 s35, s35, 0
	v_bfe_u32 v142, v136, 6, 1
	v_lshlrev_b32_e32 v142, 16, v142
	v_lshl_or_b32 v142, v137, 12, v142
	v_lshl_or_b32 v142, v139, 7, v142
	v_lshl_or_b32 v142, v138, 3, v142
	v_add_u32_e32 v143, 0x8000, v142
	global_load_dwordx2 v[112:113], v142, s[34:35] nt
	global_load_dwordx2 v[132:133], v143, s[34:35] nt
	global_load_dwordx2 v[116:117], v142, s[34:35] offset:512 nt
	global_load_dwordx2 v[130:131], v143, s[34:35] offset:512 nt
	global_load_dwordx2 v[134:135], v142, s[34:35] offset:1024 nt
	global_load_dwordx2 v[128:129], v143, s[34:35] offset:1024 nt
	global_load_dwordx2 v[114:115], v142, s[34:35] offset:1536 nt
	global_load_dwordx2 v[126:127], v143, s[34:35] offset:1536 nt
	s_and_saveexec_b64 s[0:1], vcc
	s_xor_b64 s[0:1], exec, s[0:1]
	v_lshlrev_b32_e32 v1, 1, v136
	s_or_saveexec_b64 s[0:1], s[0:1]
	v_mov_b32_e32 v3, 0
	s_xor_b64 exec, exec, s[0:1]
	s_cbranch_execz .LBB0_782
	v_readlane_b32 s7, v255, 35
	v_add_u32_e32 v2, -1, v0
	v_mov_b32_e32 v3, 0
	v_add_u32_e32 v4, s7, v1
	s_mov_b64 s[12:13], 0

.Lscan_done:
	s_add_u32 s6, s10, 0xfe01000
	s_addc_u32 s7, s11, 0
	s_ashr_i32 s42, s5, 7
	s_lshr_b32 s8, s5, 5
	s_and_b32 s22, s5, 0xffffff80
	s_add_i32 s0, s42, s2
	s_and_b32 s70, s8, 2
	s_lshl_b32 s8, s22, 1
	s_ashr_i32 s1, s0, 31
	s_add_i32 s8, s8, 0
	s_lshl_b32 s68, s70, 4
	v_bfe_u32 v34, v136, 4, 2
	s_lshl_b64 s[0:1], s[0:1], 15
	s_add_i32 s8, s8, 0x13c00
	s_or_b32 s17, s68, 16
	v_and_b32_e32 v206, 15, v136
	v_lshlrev_b32_e32 v32, 4, v34
	s_add_u32 s0, s10, s0
	v_add_u32_e32 v0, s8, v32
	v_or_b32_e32 v212, s68, v206
	s_movk_i32 s8, 0x410
	s_addc_u32 s1, s11, s1
	v_mov_b32_e32 v33, v197
	v_mad_u32_u24 v1, v212, s8, v0
	v_lshl_add_u64 v[32:33], s[0:1], 0, v[32:33]
	s_mov_b64 s[0:1], 0x3800000
	s_ashr_i32 s39, s38, 31
	s_barrier
	ds_read_b128 v[28:31], v1
	ds_read_b128 v[24:27], v1 offset:64
	ds_read_b128 v[20:23], v1 offset:128
	ds_read_b128 v[16:19], v1 offset:192
	v_or_b32_e32 v1, s17, v206
	v_lshlrev_b32_e32 v207, 3, v34
	v_lshl_add_u64 v[120:121], v[32:33], 0, s[0:1]
	v_lshlrev_b32_e32 v208, 2, v34
	v_lshl_add_u64 v[34:35], s[10:11], 0, v[196:197]
	s_mov_b64 s[0:1], 0x1c801000
	s_or_b32 s12, s38, s68
	s_mov_b32 s13, s39
	v_mad_u32_u24 v0, v1, s8, v0
	v_lshl_add_u64 v[118:119], v[34:35], 0, s[0:1]
	s_lshl_b64 s[0:1], s[12:13], 2
	s_ashr_i32 s8, s22, 4
	s_and_b32 s20, s1, 0x7fffff
	s_and_b32 s21, s0, 0xffffff80
	s_ashr_i32 s9, s8, 31
	s_add_u32 s0, s21, s8
	v_or_b32_e32 v32, s22, v208
	s_addc_u32 s1, s20, s9
	v_ashrrev_i32_e32 v33, 31, v32
	s_lshl_b64 s[0:1], s[0:1], 9
	s_or_b32 s10, s38, s17
	s_mov_b32 s11, s39
	v_lshl_add_u64 v[122:123], v[32:33], 2, s[66:67]
	v_lshl_add_u64 v[32:33], v[118:119], 0, s[0:1]
	s_lshl_b64 s[0:1], s[10:11], 2
	s_and_b32 s24, s1, 0x7fffff
	s_and_b32 s25, s0, 0xffffffc0
	s_add_u32 s0, s25, s8
	v_lshlrev_b32_e32 v34, 8, v206
	v_mov_b32_e32 v35, v197
	s_addc_u32 s1, s24, s9
	v_lshl_add_u64 v[124:125], v[120:121], 0, v[34:35]
	s_lshl_b64 s[0:1], s[0:1], 9
	ds_read_b128 v[12:15], v0
	ds_read_b128 v[8:11], v0 offset:64
	ds_read_b128 v[4:7], v0 offset:128
	ds_read_b128 v[0:3], v0 offset:192
	v_lshl_add_u64 v[32:33], v[118:119], 0, s[0:1]
	s_or_b32 s0, s22, 16
	s_ashr_i32 s8, s0, 4
	s_ashr_i32 s9, s8, 31
	v_or_b32_e32 v210, 16, v206
	s_add_u32 s0, s21, s8
	v_lshlrev_b32_e32 v32, 8, v210
	v_mov_b32_e32 v33, v197
	s_addc_u32 s1, s20, s9
	v_lshl_add_u64 v[32:33], v[120:121], 0, v[32:33]
	s_lshl_b64 s[0:1], s[0:1], 9
	v_lshl_add_u64 v[32:33], v[118:119], 0, s[0:1]
	s_add_u32 s0, s25, s8
	s_addc_u32 s1, s24, s9
	s_lshl_b64 s[0:1], s[0:1], 9
	v_lshl_add_u64 v[32:33], v[118:119], 0, s[0:1]
	s_or_b32 s0, s22, 32
	s_ashr_i32 s8, s0, 4
	s_ashr_i32 s9, s8, 31
	v_or_b32_e32 v211, 32, v206
	s_add_u32 s0, s21, s8
	v_lshlrev_b32_e32 v32, 8, v211
	v_mov_b32_e32 v33, v197
	s_addc_u32 s1, s20, s9
	v_lshl_add_u64 v[32:33], v[120:121], 0, v[32:33]
	s_lshl_b64 s[0:1], s[0:1], 9
	v_lshl_add_u64 v[32:33], v[118:119], 0, s[0:1]
	s_add_u32 s0, s25, s8
	s_addc_u32 s1, s24, s9
	s_lshl_b64 s[0:1], s[0:1], 9
	v_lshl_add_u64 v[32:33], v[118:119], 0, s[0:1]
	s_or_b32 s0, s22, 48
	s_ashr_i32 s8, s0, 4
	s_ashr_i32 s9, s8, 31
	s_add_u32 s0, s21, s8
	v_or_b32_e32 v209, 48, v206
	s_addc_u32 s1, s20, s9
	v_lshlrev_b32_e32 v32, 8, v209
	v_mov_b32_e32 v33, v197
	s_lshl_b64 s[0:1], s[0:1], 9
	v_lshl_add_u64 v[32:33], v[120:121], 0, v[32:33]
	s_add_u32 s0, s25, s8
	s_addc_u32 s1, s24, s9
	s_lshl_b64 s[0:1], s[0:1], 9
	v_and_b32_e32 v137, 4, v208
	s_nop 0
	s_waitcnt vmcnt(0) lgkmcnt(7)
	v_mov_b32_e32 v32, v148
	v_mov_b32_e32 v33, v149
	v_mov_b32_e32 v34, v150
	v_mov_b32_e32 v35, v151
	v_mfma_f32_16x16x32_bf16 v[138:141], v[108:111], v[28:31], 0
	s_waitcnt vmcnt(23)
	v_lshlrev_b32_e32 v142, 16, v112
	v_lshlrev_b32_e32 v144, 16, v113
	v_and_b32_e32 v146, 0xffff0000, v113
	s_waitcnt lgkmcnt(6)
	v_mfma_f32_16x16x32_bf16 v[138:141], v[104:107], v[24:27], v[138:141]
	v_mul_f32_e32 v113, 0xbfb8aa3b, v142
	v_exp_f32_e32 v113, v113
	v_and_b32_e32 v112, 0xffff0000, v112
	s_waitcnt lgkmcnt(5)
	v_mfma_f32_16x16x32_bf16 v[138:141], v[100:103], v[20:23], v[138:141]
	s_waitcnt vmcnt(21)
	v_mov_b32_e32 v149, v92
	v_add_f32_e32 v113, 1.0, v113
	v_rcp_f32_e32 v148, v113
	s_waitcnt lgkmcnt(4)
	v_mfma_f32_16x16x32_bf16 v[138:141], v[96:99], v[16:19], v[138:141]
	v_mul_f32_e32 v113, 0xbfb8aa3b, v112
	v_exp_f32_e32 v113, v113
	s_lshl_b64 s[0:1], s[12:13], 1
	s_ashr_i32 s26, s22, 5
	s_and_b32 s13, s1, 0x3fffff
	s_nop 2
	v_mov_b32_e32 v143, v138
	v_pk_mul_f32 v[142:143], v[148:149], v[142:143]
	v_add_f32_e32 v113, 1.0, v113
	v_mul_f32_e32 v138, v142, v143
	v_rcp_f32_e32 v142, v113
	v_mov_b32_e32 v143, v93
	v_mov_b32_e32 v113, v139
	v_mov_b32_e32 v145, v140
	v_pk_mul_f32 v[112:113], v[142:143], v[112:113]
	s_and_b32 s19, s0, 0xffffffc0
	v_mul_f32_e32 v112, v112, v113
	v_cvt_pk_bf16_f32 v138, v138, v112
	v_mul_f32_e32 v112, 0xbfb8aa3b, v144
	v_exp_f32_e32 v112, v112
	v_mov_b32_e32 v113, v94
	v_mov_b32_e32 v147, v141
	s_ashr_i32 s27, s26, 31
	v_add_f32_e32 v112, 1.0, v112
	v_rcp_f32_e32 v112, v112
	s_add_u32 s0, s19, s26
	s_addc_u32 s1, s13, s27
	s_lshl_b64 s[0:1], s[0:1], 10
	v_pk_mul_f32 v[112:113], v[112:113], v[144:145]
	s_add_u32 s0, s6, s0
	v_mul_f32_e32 v139, v112, v113
	v_mul_f32_e32 v112, 0xbfb8aa3b, v146
	v_exp_f32_e32 v112, v112
	v_mov_b32_e32 v113, v95
	s_addc_u32 s1, s7, s1
	v_lshlrev_b32_e32 v184, 1, v137
	v_add_f32_e32 v112, 1.0, v112
	v_rcp_f32_e32 v112, v112
	v_mov_b32_e32 v185, v197
	s_waitcnt vmcnt(16)
	v_lshlrev_b32_e32 v142, 16, v116
	v_lshlrev_b32_e32 v144, 16, v117
	v_pk_mul_f32 v[112:113], v[112:113], v[146:147]
	v_and_b32_e32 v146, 0xffff0000, v117
	v_mul_f32_e32 v112, v112, v113
	v_cvt_pk_bf16_f32 v139, v139, v112
	v_lshrrev_b32_e32 v112, 1, v136
	v_and_or_b32 v112, v112, 16, v206
	v_lshlrev_b32_e32 v112, 4, v112
	v_mov_b32_e32 v113, v197
	v_lshl_add_u64 v[140:141], s[0:1], 0, v[112:113]
	v_lshl_add_u64 v[140:141], v[140:141], 0, v[184:185]
	global_store_dwordx2 v[140:141], v[138:139], off
	v_mfma_f32_16x16x32_bf16 v[138:141], v[88:91], v[28:31], 0
	v_mul_f32_e32 v117, 0xbfb8aa3b, v142
	v_exp_f32_e32 v117, v117
	v_and_b32_e32 v116, 0xffff0000, v116
	v_mfma_f32_16x16x32_bf16 v[138:141], v[84:87], v[24:27], v[138:141]
	s_waitcnt vmcnt(15)
	v_mov_b32_e32 v149, v72
	v_add_f32_e32 v117, 1.0, v117
	v_rcp_f32_e32 v148, v117
	v_mfma_f32_16x16x32_bf16 v[138:141], v[80:83], v[20:23], v[138:141]
	v_mul_f32_e32 v117, 0xbfb8aa3b, v116
	v_exp_f32_e32 v117, v117
	v_or_b32_e32 v213, 16, v208
	v_mfma_f32_16x16x32_bf16 v[138:141], v[76:79], v[16:19], v[138:141]
	s_or_b32 s33, s26, 1
	v_add_f32_e32 v117, 1.0, v117
	s_ashr_i32 s34, s33, 31
	s_waitcnt lgkmcnt(3)
	v_mfma_f32_16x16x32_bf16 v[108:111], v[108:111], v[12:15], 0
	v_or_b32_e32 v222, 48, v208
	s_nop 1
	v_mov_b32_e32 v143, v138
	v_pk_mul_f32 v[142:143], v[148:149], v[142:143]
	v_mov_b32_e32 v145, v140
	v_mul_f32_e32 v137, v142, v143
	v_rcp_f32_e32 v142, v117
	v_mov_b32_e32 v143, v73
	v_mov_b32_e32 v117, v139
	v_mov_b32_e32 v147, v141
	v_pk_mul_f32 v[116:117], v[142:143], v[116:117]
	s_waitcnt vmcnt(10)
	v_lshlrev_b32_e32 v142, 16, v134
	v_mul_f32_e32 v116, v116, v117
	v_cvt_pk_bf16_f32 v138, v137, v116
	v_mul_f32_e32 v116, 0xbfb8aa3b, v144
	v_exp_f32_e32 v116, v116
	v_mov_b32_e32 v117, v74
	v_and_b32_e32 v134, 0xffff0000, v134
	s_waitcnt vmcnt(8)
	v_mov_b32_e32 v149, v52
	v_add_f32_e32 v116, 1.0, v116
	v_rcp_f32_e32 v116, v116
	s_waitcnt lgkmcnt(2)
	v_mfma_f32_16x16x32_bf16 v[104:107], v[104:107], v[8:11], v[108:111]
	v_or_b32_e32 v238, 0x60, v206
	v_or_b32_e32 v223, 0x70, v206
	v_pk_mul_f32 v[116:117], v[116:117], v[144:145]
	v_lshlrev_b32_e32 v144, 16, v135
	v_mul_f32_e32 v137, v116, v117
	v_mul_f32_e32 v116, 0xbfb8aa3b, v146
	v_exp_f32_e32 v116, v116
	v_mov_b32_e32 v117, v75
	s_waitcnt lgkmcnt(1)
	v_mfma_f32_16x16x32_bf16 v[100:103], v[100:103], v[4:7], v[104:107]
	v_mov_b32_e32 v109, v92
	v_add_f32_e32 v116, 1.0, v116
	v_rcp_f32_e32 v116, v116
	v_mfma_f32_16x16x32_bf16 v[88:91], v[88:91], v[12:15], 0
	v_lshlrev_b32_e32 v104, 16, v133
	v_and_b32_e32 v106, 0xffff0000, v133
	v_pk_mul_f32 v[116:117], v[116:117], v[146:147]
	v_and_b32_e32 v146, 0xffff0000, v135
	v_mul_f32_e32 v116, v116, v117
	v_cvt_pk_bf16_f32 v139, v137, v116
	v_lshlrev_b32_e32 v116, 1, v213
	v_and_or_b32 v116, v116, 48, v206
	v_lshlrev_b32_e32 v116, 4, v116
	v_mov_b32_e32 v117, v197
	v_lshl_add_u64 v[140:141], s[0:1], 0, v[116:117]
	v_lshl_add_u64 v[140:141], v[140:141], 0, v[184:185]
	global_store_dwordx2 v[140:141], v[138:139], off
	v_mfma_f32_16x16x32_bf16 v[138:141], v[68:71], v[28:31], 0
	v_mul_f32_e32 v135, 0xbfb8aa3b, v142
	v_exp_f32_e32 v135, v135
	s_add_u32 s0, s19, s33
	v_mfma_f32_16x16x32_bf16 v[138:141], v[64:67], v[24:27], v[138:141]
	s_addc_u32 s1, s13, s34
	v_add_f32_e32 v135, 1.0, v135
	v_rcp_f32_e32 v148, v135
	v_mfma_f32_16x16x32_bf16 v[138:141], v[60:63], v[20:23], v[138:141]
	v_mul_f32_e32 v135, 0xbfb8aa3b, v134
	v_exp_f32_e32 v135, v135
	s_lshl_b64 s[0:1], s[0:1], 10
	v_mfma_f32_16x16x32_bf16 v[138:141], v[56:59], v[16:19], v[138:141]
	s_add_u32 s0, s6, s0
	v_add_f32_e32 v135, 1.0, v135
	s_addc_u32 s1, s7, s1
	s_waitcnt lgkmcnt(0)
	v_mfma_f32_16x16x32_bf16 v[96:99], v[96:99], v[0:3], v[100:103]
	s_nop 2
	v_and_b32_e32 v102, 0xffff0000, v132
	v_mov_b32_e32 v143, v138
	v_pk_mul_f32 v[142:143], v[148:149], v[142:143]
	v_mov_b32_e32 v145, v140
	v_mul_f32_e32 v137, v142, v143
	v_rcp_f32_e32 v142, v135
	v_mov_b32_e32 v143, v53
	v_mov_b32_e32 v135, v139
	v_mov_b32_e32 v139, v54
	v_pk_mul_f32 v[134:135], v[142:143], v[134:135]
	v_mov_b32_e32 v147, v141
	v_mul_f32_e32 v134, v134, v135
	v_mul_f32_e32 v135, 0xbfb8aa3b, v144
	v_exp_f32_e32 v135, v135
	v_cvt_pk_bf16_f32 v134, v137, v134
	v_mul_f32_e32 v137, 0xbfb8aa3b, v146
	v_exp_f32_e32 v137, v137
	v_add_f32_e32 v135, 1.0, v135
	v_rcp_f32_e32 v138, v135
	s_waitcnt vmcnt(2)
	v_lshlrev_b32_e32 v142, 16, v115
	v_add_f32_e32 v137, 1.0, v137
	v_mfma_f32_16x16x32_bf16 v[84:87], v[84:87], v[8:11], v[88:91]
	v_mul_f32_e64 v138, v138, v144
	v_mul_f32_e64 v139, v139, v145
	v_and_b32_e32 v144, 0xffff0000, v115
	v_mul_f32_e32 v135, v138, v139
	v_rcp_f32_e32 v138, v137
	v_mov_b32_e32 v139, v55
	v_mul_f32_e32 v92, 0xbfb8aa3b, v102
	v_exp_f32_e32 v92, v92
	v_pk_mul_f32 v[138:139], v[138:139], v[146:147]
	v_mov_b32_e32 v147, v32
	v_mul_f32_e32 v137, v138, v139
	v_lshl_add_u64 v[138:139], s[0:1], 0, v[112:113]
	v_lshl_add_u64 v[138:139], v[138:139], 0, v[184:185]
	v_cvt_pk_bf16_f32 v135, v135, v137
	global_store_dwordx2 v[138:139], v[134:135], off
	v_mfma_f32_16x16x32_bf16 v[138:141], v[48:51], v[28:31], 0
	v_lshlrev_b32_e32 v134, 16, v114
	v_mul_f32_e32 v115, 0xbfb8aa3b, v134
	v_exp_f32_e32 v115, v115
	v_mfma_f32_16x16x32_bf16 v[138:141], v[44:47], v[24:27], v[138:141]
	v_and_b32_e32 v114, 0xffff0000, v114
	v_lshlrev_b32_e32 v100, 16, v132
	v_add_f32_e32 v115, 1.0, v115
	v_mfma_f32_16x16x32_bf16 v[138:141], v[40:43], v[20:23], v[138:141]
	v_rcp_f32_e32 v146, v115
	v_mul_f32_e32 v115, 0xbfb8aa3b, v114
	v_exp_f32_e32 v115, v115
	v_mfma_f32_16x16x32_bf16 v[138:141], v[36:39], v[16:19], v[138:141]
	v_mul_f32_e32 v101, 0xbfb8aa3b, v100
	v_add_f32_e32 v92, 1.0, v92
	v_add_f32_e32 v115, 1.0, v115
	v_mfma_f32_16x16x32_bf16 v[80:83], v[80:83], v[4:7], v[84:87]
	v_exp_f32_e32 v101, v101
	s_nop 2
	v_mov_b32_e32 v135, v138
	v_pk_mul_f32 v[134:135], v[146:147], v[134:135]
	v_mov_b32_e32 v143, v140
	v_mul_f32_e32 v137, v134, v135
	v_rcp_f32_e32 v134, v115
	v_mov_b32_e32 v135, v33
	v_mov_b32_e32 v115, v139
	v_mfma_f32_16x16x32_bf16 v[68:71], v[68:71], v[12:15], 0
	v_mul_f32_e64 v114, v134, v114
	v_mul_f32_e64 v115, v135, v115
	v_rcp_f32_e32 v92, v92
	v_mul_f32_e32 v114, v114, v115
	v_cvt_pk_bf16_f32 v134, v137, v114
	v_mul_f32_e32 v114, 0xbfb8aa3b, v142
	v_exp_f32_e32 v114, v114
	v_mov_b32_e32 v115, v34
	v_mfma_f32_16x16x32_bf16 v[76:79], v[76:79], v[0:3], v[80:83]
	v_mov_b32_e32 v89, v72
	v_add_f32_e32 v114, 1.0, v114
	v_rcp_f32_e32 v114, v114
	v_and_b32_e32 v82, 0xffff0000, v130
	v_mfma_f32_16x16x32_bf16 v[64:67], v[64:67], v[8:11], v[68:71]
	v_mul_f32_e32 v72, 0xbfb8aa3b, v82
	v_pk_mul_f32 v[114:115], v[114:115], v[142:143]
	v_mov_b32_e32 v145, v141
	v_mul_f32_e32 v135, v114, v115
	v_mul_f32_e32 v114, 0xbfb8aa3b, v144
	v_exp_f32_e32 v114, v114
	v_mov_b32_e32 v115, v35
	v_mov_b32_e32 v103, v97
	v_exp_f32_e32 v72, v72
	v_add_f32_e32 v114, 1.0, v114
	v_rcp_f32_e32 v114, v114
	v_add_f32_e32 v101, 1.0, v101
	v_pk_mul_f32 v[92:93], v[92:93], v[102:103]
	v_rcp_f32_e32 v108, v101
	v_pk_mul_f32 v[114:115], v[114:115], v[144:145]
	v_mul_f32_e32 v92, v92, v93
	v_mul_f32_e32 v114, v114, v115
	v_mul_f32_e32 v93, 0xbfb8aa3b, v104
	v_mov_b32_e32 v97, v94
	v_mul_f32_e32 v94, 0xbfb8aa3b, v106
	v_mfma_f32_16x16x32_bf16 v[60:63], v[60:63], v[4:7], v[64:67]
	v_cvt_pk_bf16_f32 v135, v135, v114
	v_lshlrev_b32_e32 v114, 1, v222
	v_exp_f32_e32 v93, v93
	v_mfma_f32_16x16x32_bf16 v[48:51], v[48:51], v[12:15], 0
	v_exp_f32_e32 v94, v94
	v_lshlrev_b32_e32 v80, 16, v130
	v_and_or_b32 v114, v114, 48, v206
	v_mul_f32_e32 v81, 0xbfb8aa3b, v80
	v_add_f32_e32 v72, 1.0, v72
	v_lshlrev_b32_e32 v114, 4, v114
	v_mov_b32_e32 v115, v197
	v_mov_b32_e32 v101, v96
	v_exp_f32_e32 v81, v81
	v_rcp_f32_e32 v72, v72
	v_lshl_add_u64 v[138:139], s[0:1], 0, v[114:115]
	v_pk_mul_f32 v[100:101], v[108:109], v[100:101]
	v_mfma_f32_16x16x32_bf16 v[56:59], v[56:59], v[0:3], v[60:63]
	v_lshl_add_u64 v[138:139], v[138:139], 0, v[184:185]
	s_lshl_b64 s[0:1], s[10:11], 1
	v_mul_f32_e32 v96, v100, v101
	v_and_b32_e32 v62, 0xffff0000, v128
	v_mfma_f32_16x16x32_bf16 v[44:47], v[44:47], v[8:11], v[48:51]
	v_add_f32_e32 v93, 1.0, v93
	v_add_f32_e32 v94, 1.0, v94
	v_mov_b32_e32 v69, v52
	v_mul_f32_e32 v52, 0xbfb8aa3b, v62
	global_store_dwordx2 v[138:139], v[134:135], off
	s_and_b32 s8, s1, 0x3fffff
	s_and_b32 s9, s0, 0xffffffe0
	v_cvt_pk_bf16_f32 v92, v96, v92
	v_rcp_f32_e32 v96, v93
	v_rcp_f32_e32 v94, v94
	v_mov_b32_e32 v83, v77
	v_exp_f32_e32 v52, v52
	s_add_u32 s0, s9, s26
	v_lshlrev_b32_e32 v84, 16, v131
	v_and_b32_e32 v86, 0xffff0000, v131
	v_add_f32_e32 v81, 1.0, v81
	v_pk_mul_f32 v[72:73], v[72:73], v[82:83]
	s_addc_u32 s1, s8, s27
	v_rcp_f32_e32 v88, v81
	v_mul_f32_e32 v72, v72, v73
	v_mul_f32_e32 v73, 0xbfb8aa3b, v84
	v_mov_b32_e32 v77, v74
	v_mul_f32_e32 v74, 0xbfb8aa3b, v86
	v_mfma_f32_16x16x32_bf16 v[40:43], v[40:43], v[4:7], v[44:47]
	v_mov_b32_e32 v105, v98
	v_mov_b32_e32 v107, v99
	s_lshl_b64 s[0:1], s[0:1], 10
	v_exp_f32_e32 v73, v73
	v_exp_f32_e32 v74, v74
	v_lshlrev_b32_e32 v60, 16, v128
	v_pk_mul_f32 v[96:97], v[96:97], v[104:105]
	v_pk_mul_f32 v[94:95], v[94:95], v[106:107]
	s_add_u32 s0, s6, s0
	v_mul_f32_e32 v61, 0xbfb8aa3b, v60
	v_add_f32_e32 v52, 1.0, v52
	v_mul_f32_e32 v93, v96, v97
	v_mul_f32_e32 v94, v94, v95
	s_addc_u32 s1, s7, s1
	v_mov_b32_e32 v81, v76
	v_exp_f32_e32 v61, v61
	v_rcp_f32_e32 v52, v52
	v_cvt_pk_bf16_f32 v93, v93, v94
	v_lshl_add_u64 v[94:95], s[0:1], 0, v[112:113]
	v_pk_mul_f32 v[80:81], v[88:89], v[80:81]
	v_mfma_f32_16x16x32_bf16 v[36:39], v[36:39], v[0:3], v[40:43]
	v_lshl_add_u64 v[94:95], v[94:95], 0, v[184:185]
	v_mul_f32_e32 v76, v80, v81
	v_add_f32_e32 v73, 1.0, v73
	s_waitcnt vmcnt(4)
	v_and_b32_e32 v42, 0xffff0000, v126
	v_add_f32_e32 v74, 1.0, v74
	v_mov_b32_e32 v49, v32
	v_mul_f32_e32 v32, 0xbfb8aa3b, v42
	global_store_dwordx2 v[94:95], v[92:93], off
	v_cvt_pk_bf16_f32 v72, v76, v72
	v_rcp_f32_e32 v76, v73
	v_rcp_f32_e32 v74, v74
	v_mov_b32_e32 v63, v57
	v_exp_f32_e32 v32, v32
	v_lshlrev_b32_e32 v64, 16, v129
	v_and_b32_e32 v66, 0xffff0000, v129
	v_add_f32_e32 v61, 1.0, v61
	v_pk_mul_f32 v[52:53], v[52:53], v[62:63]
	v_rcp_f32_e32 v68, v61
	v_mul_f32_e32 v52, v52, v53
	v_mul_f32_e32 v53, 0xbfb8aa3b, v64
	v_mov_b32_e32 v57, v54
	v_mul_f32_e32 v54, 0xbfb8aa3b, v66
	v_mov_b32_e32 v85, v78
	v_mov_b32_e32 v87, v79
	v_exp_f32_e32 v53, v53
	v_exp_f32_e32 v54, v54
	v_lshlrev_b32_e32 v40, 16, v126
	v_pk_mul_f32 v[76:77], v[76:77], v[84:85]
	v_pk_mul_f32 v[74:75], v[74:75], v[86:87]
	v_mul_f32_e32 v41, 0xbfb8aa3b, v40
	v_add_f32_e32 v32, 1.0, v32
	v_mul_f32_e32 v73, v76, v77
	v_mul_f32_e32 v74, v74, v75
	v_mov_b32_e32 v61, v56
	v_exp_f32_e32 v41, v41
	v_rcp_f32_e32 v32, v32
	v_cvt_pk_bf16_f32 v73, v73, v74
	v_lshl_add_u64 v[74:75], s[0:1], 0, v[116:117]
	v_pk_mul_f32 v[60:61], v[68:69], v[60:61]
	v_lshl_add_u64 v[74:75], v[74:75], 0, v[184:185]
	v_mul_f32_e32 v56, v60, v61
	v_add_f32_e32 v53, 1.0, v53
	v_add_f32_e32 v54, 1.0, v54
	global_store_dwordx2 v[74:75], v[72:73], off
	v_cvt_pk_bf16_f32 v52, v56, v52
	v_rcp_f32_e32 v56, v53
	v_rcp_f32_e32 v54, v54
	v_mov_b32_e32 v43, v37
	s_add_u32 s0, s9, s33
	v_lshlrev_b32_e32 v44, 16, v127
	v_and_b32_e32 v46, 0xffff0000, v127
	v_add_f32_e32 v41, 1.0, v41
	v_pk_mul_f32 v[32:33], v[32:33], v[42:43]
	s_addc_u32 s1, s8, s34
	v_rcp_f32_e32 v48, v41
	v_mul_f32_e32 v32, v32, v33
	v_mul_f32_e32 v33, 0xbfb8aa3b, v44
	v_mov_b32_e32 v37, v34
	v_mul_f32_e32 v34, 0xbfb8aa3b, v46
	v_mov_b32_e32 v65, v58
	v_mov_b32_e32 v67, v59
	s_lshl_b64 s[0:1], s[0:1], 10
	v_exp_f32_e32 v33, v33
	v_exp_f32_e32 v34, v34
	v_pk_mul_f32 v[56:57], v[56:57], v[64:65]
	v_pk_mul_f32 v[54:55], v[54:55], v[66:67]
	s_add_u32 s0, s6, s0
	v_mul_f32_e32 v53, v56, v57
	v_mul_f32_e32 v54, v54, v55
	s_addc_u32 s1, s7, s1
	v_mov_b32_e32 v41, v36
	v_cvt_pk_bf16_f32 v53, v53, v54
	v_lshl_add_u64 v[54:55], s[0:1], 0, v[112:113]
	v_pk_mul_f32 v[40:41], v[48:49], v[40:41]
	v_lshl_add_u64 v[54:55], v[54:55], 0, v[184:185]
	v_mul_f32_e32 v36, v40, v41
	v_add_f32_e32 v33, 1.0, v33
	v_add_f32_e32 v34, 1.0, v34
	global_store_dwordx2 v[54:55], v[52:53], off
	v_cvt_pk_bf16_f32 v32, v36, v32
	v_rcp_f32_e32 v36, v33
	v_rcp_f32_e32 v34, v34
	v_mov_b32_e32 v45, v38
	v_mov_b32_e32 v47, v39
	v_pk_mul_f32 v[36:37], v[36:37], v[44:45]
	v_pk_mul_f32 v[34:35], v[34:35], v[46:47]
	v_mul_f32_e32 v33, v36, v37
	v_mul_f32_e32 v34, v34, v35
	v_cvt_pk_bf16_f32 v33, v33, v34
	v_lshl_add_u64 v[34:35], s[0:1], 0, v[114:115]
	v_lshl_add_u64 v[34:35], v[34:35], 0, v[184:185]
	global_store_dwordx2 v[34:35], v[32:33], off
	v_add_co_u32_e32 v32, vcc, s71, v124
	s_movk_i32 s0, 0x5000
	s_nop 0
	v_addc_co_u32_e32 v33, vcc, 0, v125, vcc
	v_add_co_u32_e32 v34, vcc, s0, v124
	s_or_b32 s0, s22, 64
	s_ashr_i32 s10, s0, 4
	s_ashr_i32 s11, s10, 31
	s_add_u32 s0, s21, s10
	s_addc_u32 s1, s20, s11
	v_addc_co_u32_e32 v35, vcc, 0, v125, vcc
	s_lshl_b64 s[0:1], s[0:1], 9
	global_load_dwordx4 v[108:111], v[34:35], off offset:-4096
	global_load_dwordx4 v[104:107], v[32:33], off offset:64
	global_load_dwordx4 v[100:103], v[32:33], off offset:128
	global_load_dwordx4 v[96:99], v[32:33], off offset:192
	v_lshl_add_u64 v[32:33], v[118:119], 0, s[0:1]
	s_add_u32 s0, s25, s10
	s_addc_u32 s1, s24, s11
	s_lshl_b64 s[0:1], s[0:1], 9
	global_load_dwordx2 v[134:135], v[32:33], off nt
	v_lshl_add_u64 v[32:33], v[118:119], 0, s[0:1]
	s_or_b32 s0, s22, 0x50
	s_ashr_i32 s10, s0, 4
	s_ashr_i32 s11, s10, 31
	s_add_u32 s0, s21, s10
	s_addc_u32 s1, s20, s11
	s_lshl_b64 s[0:1], s[0:1], 9
	global_load_dwordx4 v[92:95], v[122:123], off offset:256
	global_load_dwordx2 v[128:129], v[32:33], off nt
	global_load_dwordx4 v[88:91], v[34:35], off
	global_load_dwordx4 v[84:87], v[34:35], off offset:64
	global_load_dwordx4 v[80:83], v[34:35], off offset:128
	global_load_dwordx4 v[76:79], v[34:35], off offset:192
	v_lshl_add_u64 v[32:33], v[118:119], 0, s[0:1]
	s_add_u32 s0, s25, s10
	s_addc_u32 s1, s24, s11
	s_lshl_b64 s[0:1], s[0:1], 9
	global_load_dwordx2 v[132:133], v[32:33], off nt
	v_lshl_add_u64 v[32:33], v[118:119], 0, s[0:1]
	s_or_b32 s0, s22, 0x60
	s_ashr_i32 s10, s0, 4
	s_ashr_i32 s11, s10, 31
	s_add_u32 s0, s21, s10
	global_load_dwordx2 v[126:127], v[32:33], off nt
	v_lshlrev_b32_e32 v32, 8, v238
	v_mov_b32_e32 v33, v197
	s_addc_u32 s1, s20, s11
	v_lshl_add_u64 v[32:33], v[120:121], 0, v[32:33]
	s_lshl_b64 s[0:1], s[0:1], 9
	global_load_dwordx4 v[72:75], v[122:123], off offset:320
	global_load_dwordx4 v[68:71], v[32:33], off
	global_load_dwordx4 v[64:67], v[32:33], off offset:64
	global_load_dwordx4 v[60:63], v[32:33], off offset:128
	global_load_dwordx4 v[56:59], v[32:33], off offset:192
	v_lshl_add_u64 v[32:33], v[118:119], 0, s[0:1]
	s_add_u32 s0, s25, s10
	s_addc_u32 s1, s24, s11
	s_lshl_b64 s[0:1], s[0:1], 9
	global_load_dwordx2 v[130:131], v[32:33], off nt
	v_lshl_add_u64 v[32:33], v[118:119], 0, s[0:1]
	s_or_b32 s0, s22, 0x70
	s_ashr_i32 s10, s0, 4
	s_ashr_i32 s11, s10, 31
	s_add_u32 s0, s21, s10
	s_addc_u32 s1, s20, s11
	global_load_dwordx2 v[124:125], v[32:33], off nt
	v_lshlrev_b32_e32 v32, 8, v223
	v_mov_b32_e32 v33, v197
	s_lshl_b64 s[0:1], s[0:1], 9
	v_lshl_add_u64 v[32:33], v[120:121], 0, v[32:33]
	v_lshl_add_u64 v[120:121], v[118:119], 0, s[0:1]
	s_add_u32 s0, s25, s10
	global_load_dwordx4 v[52:55], v[122:123], off offset:384
	global_load_dwordx4 v[48:51], v[32:33], off
	global_load_dwordx4 v[44:47], v[32:33], off offset:64
	global_load_dwordx4 v[40:43], v[32:33], off offset:128
	global_load_dwordx4 v[36:39], v[32:33], off offset:192
	s_addc_u32 s1, s24, s11
	s_lshl_b64 s[0:1], s[0:1], 9
	v_lshl_add_u64 v[118:119], v[118:119], 0, s[0:1]
	global_load_dwordx4 v[32:35], v[122:123], off offset:448
	s_nop 0
	global_load_dwordx2 v[120:121], v[120:121], off nt
	s_nop 0
	global_load_dwordx2 v[118:119], v[118:119], off nt
	s_waitcnt vmcnt(27)
	v_mfma_f32_16x16x32_bf16 v[138:141], v[108:111], v[28:31], 0
	s_waitcnt vmcnt(23)
	v_lshlrev_b32_e32 v122, 16, v134
	v_mul_f32_e32 v123, 0xbfb8aa3b, v122
	v_exp_f32_e32 v123, v123
	v_mfma_f32_16x16x32_bf16 v[138:141], v[104:107], v[24:27], v[138:141]
	s_waitcnt vmcnt(22)
	v_mov_b32_e32 v147, v92
	v_and_b32_e32 v134, 0xffff0000, v134
	v_add_f32_e32 v123, 1.0, v123
	v_mfma_f32_16x16x32_bf16 v[138:141], v[100:103], v[20:23], v[138:141]
	v_rcp_f32_e32 v146, v123
	v_lshlrev_b32_e32 v142, 16, v135
	v_and_b32_e32 v144, 0xffff0000, v135
	v_mfma_f32_16x16x32_bf16 v[138:141], v[96:99], v[16:19], v[138:141]
	s_or_b32 s11, s26, 2
	s_ashr_i32 s20, s11, 31
	s_add_u32 s0, s19, s11
	s_addc_u32 s1, s13, s20
	s_lshl_b64 s[0:1], s[0:1], 10
	s_nop 2
	v_mov_b32_e32 v123, v138
	v_pk_mul_f32 v[122:123], v[146:147], v[122:123]
	v_mov_b32_e32 v135, v139
	v_mul_f32_e32 v137, v122, v123
	v_mul_f32_e32 v122, 0xbfb8aa3b, v134
	v_exp_f32_e32 v122, v122
	v_mov_b32_e32 v123, v93
	v_mov_b32_e32 v143, v140
	v_mov_b32_e32 v145, v141
	v_add_f32_e32 v122, 1.0, v122
	v_rcp_f32_e32 v122, v122
	s_waitcnt vmcnt(20)
	v_mfma_f32_16x16x32_bf16 v[138:141], v[88:91], v[28:31], 0
	s_add_u32 s0, s6, s0
	s_addc_u32 s1, s7, s1
	v_pk_mul_f32 v[122:123], v[122:123], v[134:135]
	v_mov_b32_e32 v135, v94
	v_mul_f32_e32 v122, v122, v123
	v_mul_f32_e32 v123, 0xbfb8aa3b, v142
	v_exp_f32_e32 v123, v123
	v_cvt_pk_bf16_f32 v122, v137, v122
	s_waitcnt vmcnt(19)
	v_mfma_f32_16x16x32_bf16 v[138:141], v[84:87], v[24:27], v[138:141]
	v_and_b32_e32 v220, 63, v136
	v_add_f32_e32 v123, 1.0, v123
	v_rcp_f32_e32 v134, v123
	s_waitcnt vmcnt(18)
	v_mfma_f32_16x16x32_bf16 v[138:141], v[80:83], v[20:23], v[138:141]
	v_lshlrev_b32_e32 v186, 4, v220
	v_lshlrev_b32_e32 v188, 1, v207
	v_pk_mul_f32 v[134:135], v[134:135], v[142:143]
	s_waitcnt vmcnt(17)
	v_mfma_f32_16x16x32_bf16 v[138:141], v[76:79], v[16:19], v[138:141]
	v_mul_f32_e32 v123, v134, v135
	v_mul_f32_e32 v134, 0xbfb8aa3b, v144
	v_exp_f32_e32 v134, v134
	v_mov_b32_e32 v135, v95
	s_waitcnt vmcnt(16)
	v_and_b32_e32 v142, 0xffff0000, v133
	s_nop 1
	v_mov_b32_e32 v143, v141
	v_add_f32_e32 v134, 1.0, v134
	v_rcp_f32_e32 v134, v134
	v_not_b32_e32 v219, v208
	v_or_b32_e32 v218, 2, v208
	v_or_b32_e32 v217, 3, v208
	v_pk_mul_f32 v[134:135], v[134:135], v[144:145]
	s_waitcnt vmcnt(14)
	v_mov_b32_e32 v145, v72
	v_mul_f32_e32 v134, v134, v135
	v_cvt_pk_bf16_f32 v123, v123, v134
	v_lshl_add_u64 v[134:135], s[0:1], 0, v[112:113]
	v_lshl_add_u64 v[134:135], v[134:135], 0, v[184:185]
	global_store_dwordx2 v[134:135], v[122:123], off
	v_lshlrev_b32_e32 v122, 16, v132
	v_mul_f32_e32 v123, 0xbfb8aa3b, v122
	v_exp_f32_e32 v123, v123
	v_and_b32_e32 v132, 0xffff0000, v132
	v_lshlrev_b32_e32 v134, 16, v133
	v_mov_b32_e32 v133, v139
	v_add_f32_e32 v123, 1.0, v123
	v_rcp_f32_e32 v144, v123
	v_mov_b32_e32 v123, v138
	s_waitcnt vmcnt(10)
	v_lshlrev_b32_e32 v138, 16, v131
	v_or_b32_e32 v216, 17, v208
	v_pk_mul_f32 v[122:123], v[144:145], v[122:123]
	v_or_b32_e32 v215, 18, v208
	v_mul_f32_e32 v135, v122, v123
	v_mul_f32_e32 v122, 0xbfb8aa3b, v132
	v_exp_f32_e32 v122, v122
	v_mov_b32_e32 v123, v73
	v_or_b32_e32 v214, 19, v208
	v_readlane_b32 s27, v255, 46
	v_add_f32_e32 v122, 1.0, v122
	v_rcp_f32_e32 v122, v122
	s_nop 0
	v_pk_mul_f32 v[122:123], v[122:123], v[132:133]
	s_nop 0
	v_mul_f32_e32 v122, v122, v123
	v_mul_f32_e32 v123, 0xbfb8aa3b, v134
	v_exp_f32_e32 v123, v123
	v_cvt_pk_bf16_f32 v122, v135, v122
	v_mov_b32_e32 v133, v74
	v_mov_b32_e32 v135, v140
	v_add_f32_e32 v123, 1.0, v123
	v_rcp_f32_e32 v132, v123
	v_and_b32_e32 v140, 0xffff0000, v131
	v_pk_mul_f32 v[132:133], v[132:133], v[134:135]
	s_nop 0
	v_mul_f32_e32 v123, v132, v133
	v_mul_f32_e32 v132, 0xbfb8aa3b, v142
	v_exp_f32_e32 v132, v132
	v_mov_b32_e32 v133, v75
	v_add_f32_e32 v132, 1.0, v132
	v_rcp_f32_e32 v132, v132
	s_nop 0
	v_pk_mul_f32 v[132:133], v[132:133], v[142:143]
	s_nop 0
	v_mul_f32_e32 v132, v132, v133
	v_cvt_pk_bf16_f32 v123, v123, v132
	v_lshl_add_u64 v[132:133], s[0:1], 0, v[116:117]
	v_lshl_add_u64 v[132:133], v[132:133], 0, v[184:185]
	global_store_dwordx2 v[132:133], v[122:123], off
	v_mfma_f32_16x16x32_bf16 v[132:135], v[68:71], v[28:31], 0
	v_lshlrev_b32_e32 v122, 16, v130
	v_mul_f32_e32 v123, 0xbfb8aa3b, v122
	v_exp_f32_e32 v123, v123
	v_mfma_f32_16x16x32_bf16 v[132:135], v[64:67], v[24:27], v[132:135]
	s_waitcnt vmcnt(9)
	v_mov_b32_e32 v143, v52
	v_and_b32_e32 v130, 0xffff0000, v130
	v_add_f32_e32 v123, 1.0, v123
	v_mfma_f32_16x16x32_bf16 v[132:135], v[60:63], v[20:23], v[132:135]
	v_rcp_f32_e32 v142, v123
	s_ashr_i32 s0, s5, 5
	s_or_b32 s5, s0, 3
	v_mfma_f32_16x16x32_bf16 v[132:135], v[56:59], v[16:19], v[132:135]
	s_ashr_i32 s10, s5, 31
	s_add_u32 s0, s19, s5
	s_addc_u32 s1, s13, s10
	s_waitcnt vmcnt(8)
	v_mfma_f32_16x16x32_bf16 v[28:31], v[48:51], v[28:31], 0
	s_lshl_b64 s[0:1], s[0:1], 10
	s_nop 1
	v_mov_b32_e32 v123, v132
	v_pk_mul_f32 v[122:123], v[142:143], v[122:123]
	s_waitcnt vmcnt(7)
	v_mfma_f32_16x16x32_bf16 v[24:27], v[44:47], v[24:27], v[28:31]
	v_mul_f32_e32 v132, v122, v123
	v_mul_f32_e32 v122, 0xbfb8aa3b, v130
	v_exp_f32_e32 v122, v122
	v_mov_b32_e32 v123, v53
	v_mov_b32_e32 v131, v133
	s_waitcnt vmcnt(6)
	v_mfma_f32_16x16x32_bf16 v[20:23], v[40:43], v[20:23], v[24:27]
	v_add_f32_e32 v122, 1.0, v122
	v_rcp_f32_e32 v122, v122
	v_mov_b32_e32 v139, v134
	s_waitcnt vmcnt(5)
	v_mfma_f32_16x16x32_bf16 v[16:19], v[36:39], v[16:19], v[20:23]
	s_waitcnt vmcnt(4)
	v_mov_b32_e32 v29, v32
	v_pk_mul_f32 v[122:123], v[122:123], v[130:131]
	v_mov_b32_e32 v131, v54
	v_mul_f32_e32 v122, v122, v123
	v_mul_f32_e32 v123, 0xbfb8aa3b, v138
	v_exp_f32_e32 v123, v123
	s_waitcnt vmcnt(3)
	v_lshlrev_b32_e32 v20, 16, v120
	v_mul_f32_e32 v21, 0xbfb8aa3b, v20
	v_exp_f32_e32 v21, v21
	v_add_f32_e32 v123, 1.0, v123
	v_rcp_f32_e32 v130, v123
	v_and_b32_e32 v22, 0xffff0000, v120
	v_add_f32_e32 v21, 1.0, v21
	v_rcp_f32_e32 v28, v21
	v_mov_b32_e32 v21, v16
	v_mul_f32_e32 v16, 0xbfb8aa3b, v22
	v_pk_mul_f32 v[130:131], v[130:131], v[138:139]
	v_exp_f32_e32 v16, v16
	v_mul_f32_e32 v123, v130, v131
	v_mul_f32_e32 v130, 0xbfb8aa3b, v140
	v_exp_f32_e32 v130, v130
	v_pk_mul_f32 v[20:21], v[28:29], v[20:21]
	v_add_f32_e32 v16, 1.0, v16
	v_mul_f32_e32 v25, v20, v21
	v_rcp_f32_e32 v20, v16
	v_add_f32_e32 v130, 1.0, v130
	v_rcp_f32_e32 v130, v130
	v_mov_b32_e32 v21, v33
	v_mov_b32_e32 v23, v17
	v_lshlrev_b32_e32 v24, 16, v121
	v_pk_mul_f32 v[16:17], v[20:21], v[22:23]
	v_mov_b32_e32 v131, v55
	v_mov_b32_e32 v141, v135
	v_mul_f32_e32 v16, v16, v17
	v_mul_f32_e32 v17, 0xbfb8aa3b, v24
	v_pk_mul_f32 v[130:131], v[130:131], v[140:141]
	s_add_u32 s0, s6, s0
	v_exp_f32_e32 v17, v17
	v_mul_f32_e32 v130, v130, v131
	s_addc_u32 s1, s7, s1
	v_cvt_pk_bf16_f32 v122, v132, v122
	v_cvt_pk_bf16_f32 v123, v123, v130
	v_lshl_add_u64 v[130:131], s[0:1], 0, v[112:113]
	v_lshl_add_u64 v[130:131], v[130:131], 0, v[184:185]
	v_and_b32_e32 v26, 0xffff0000, v121
	global_store_dwordx2 v[130:131], v[122:123], off
	v_cvt_pk_bf16_f32 v16, v25, v16
	v_add_f32_e32 v17, 1.0, v17
	v_mov_b32_e32 v25, v18
	v_mul_f32_e32 v18, 0xbfb8aa3b, v26
	v_rcp_f32_e32 v20, v17
	v_exp_f32_e32 v18, v18
	v_mov_b32_e32 v21, v34
	v_mov_b32_e32 v27, v19
	v_pk_mul_f32 v[20:21], v[20:21], v[24:25]
	v_add_f32_e32 v18, 1.0, v18
	v_mul_f32_e32 v17, v20, v21
	v_rcp_f32_e32 v20, v18
	v_mov_b32_e32 v21, v35
	v_and_b32_e32 v22, 0xffff0000, v128
	v_mov_b32_e32 v29, v92
	v_pk_mul_f32 v[18:19], v[20:21], v[26:27]
	v_lshlrev_b32_e32 v20, 16, v128
	v_mul_f32_e32 v18, v18, v19
	v_cvt_pk_bf16_f32 v17, v17, v18
	v_lshl_add_u64 v[18:19], s[0:1], 0, v[114:115]
	v_lshl_add_u64 v[18:19], v[18:19], 0, v[184:185]
	global_store_dwordx2 v[18:19], v[16:17], off
	v_mfma_f32_16x16x32_bf16 v[16:19], v[108:111], v[12:15], 0
	v_mul_f32_e32 v21, 0xbfb8aa3b, v20
	v_exp_f32_e32 v21, v21
	v_lshlrev_b32_e32 v24, 16, v129
	v_mfma_f32_16x16x32_bf16 v[16:19], v[104:107], v[8:11], v[16:19]
	v_and_b32_e32 v26, 0xffff0000, v129
	v_add_f32_e32 v21, 1.0, v21
	v_rcp_f32_e32 v28, v21
	v_mfma_f32_16x16x32_bf16 v[16:19], v[100:103], v[4:7], v[16:19]
	s_add_u32 s0, s9, s11
	s_addc_u32 s1, s8, s20
	s_lshl_b64 s[0:1], s[0:1], 10
	v_mfma_f32_16x16x32_bf16 v[16:19], v[96:99], v[0:3], v[16:19]
	s_add_u32 s0, s6, s0
	s_addc_u32 s1, s7, s1
	s_nop 5
	v_mov_b32_e32 v21, v16
	v_mul_f32_e32 v16, 0xbfb8aa3b, v22
	v_exp_f32_e32 v16, v16
	v_mov_b32_e32 v23, v17
	v_mov_b32_e32 v25, v18
	v_mul_f32_e32 v18, 0xbfb8aa3b, v26
	v_add_f32_e32 v16, 1.0, v16
	v_rcp_f32_e32 v92, v16
	v_exp_f32_e32 v18, v18
	v_pk_mul_f32 v[20:21], v[28:29], v[20:21]
	v_mov_b32_e32 v27, v19
	v_pk_mul_f32 v[16:17], v[92:93], v[22:23]
	v_mul_f32_e32 v20, v20, v21
	v_mul_f32_e32 v16, v16, v17
	v_mul_f32_e32 v17, 0xbfb8aa3b, v24
	v_exp_f32_e32 v17, v17
	v_add_f32_e32 v18, 1.0, v18
	v_cvt_pk_bf16_f32 v16, v20, v16
	v_mov_b32_e32 v21, v94
	v_add_f32_e32 v17, 1.0, v17
	v_rcp_f32_e32 v20, v17
	v_rcp_f32_e32 v94, v18
	v_and_b32_e32 v22, 0xffff0000, v126
	v_mov_b32_e32 v29, v72
	v_pk_mul_f32 v[20:21], v[20:21], v[24:25]
	v_pk_mul_f32 v[18:19], v[94:95], v[26:27]
	v_mul_f32_e32 v17, v20, v21
	v_mul_f32_e32 v18, v18, v19
	v_cvt_pk_bf16_f32 v17, v17, v18
	v_lshl_add_u64 v[18:19], s[0:1], 0, v[112:113]
	v_lshl_add_u64 v[18:19], v[18:19], 0, v[184:185]
	global_store_dwordx2 v[18:19], v[16:17], off
	v_mfma_f32_16x16x32_bf16 v[16:19], v[88:91], v[12:15], 0
	v_lshlrev_b32_e32 v20, 16, v126
	v_mul_f32_e32 v21, 0xbfb8aa3b, v20
	v_exp_f32_e32 v21, v21
	v_mfma_f32_16x16x32_bf16 v[16:19], v[84:87], v[8:11], v[16:19]
	v_lshlrev_b32_e32 v24, 16, v127
	v_and_b32_e32 v26, 0xffff0000, v127
	v_add_f32_e32 v21, 1.0, v21
	v_mfma_f32_16x16x32_bf16 v[16:19], v[80:83], v[4:7], v[16:19]
	v_rcp_f32_e32 v28, v21
	v_mfma_f32_16x16x32_bf16 v[16:19], v[76:79], v[0:3], v[16:19]
	s_nop 7
	v_mov_b32_e32 v21, v16
	v_mul_f32_e32 v16, 0xbfb8aa3b, v22
	v_exp_f32_e32 v16, v16
	v_mov_b32_e32 v23, v17
	v_mov_b32_e32 v25, v18
	v_mul_f32_e32 v18, 0xbfb8aa3b, v26
	v_add_f32_e32 v16, 1.0, v16
	v_rcp_f32_e32 v72, v16
	v_exp_f32_e32 v18, v18
	v_pk_mul_f32 v[20:21], v[28:29], v[20:21]
	v_mov_b32_e32 v27, v19
	v_pk_mul_f32 v[16:17], v[72:73], v[22:23]
	v_mul_f32_e32 v20, v20, v21
	v_mul_f32_e32 v16, v16, v17
	v_mul_f32_e32 v17, 0xbfb8aa3b, v24
	v_exp_f32_e32 v17, v17
	v_add_f32_e32 v18, 1.0, v18
	v_cvt_pk_bf16_f32 v16, v20, v16
	v_mov_b32_e32 v21, v74
	v_add_f32_e32 v17, 1.0, v17
	v_rcp_f32_e32 v20, v17
	v_rcp_f32_e32 v74, v18
	v_and_b32_e32 v22, 0xffff0000, v124
	v_mov_b32_e32 v29, v52
	v_pk_mul_f32 v[20:21], v[20:21], v[24:25]
	v_pk_mul_f32 v[18:19], v[74:75], v[26:27]
	v_mul_f32_e32 v17, v20, v21
	v_mul_f32_e32 v18, v18, v19
	v_cvt_pk_bf16_f32 v17, v17, v18
	v_lshl_add_u64 v[18:19], s[0:1], 0, v[116:117]
	v_lshl_add_u64 v[18:19], v[18:19], 0, v[184:185]
	global_store_dwordx2 v[18:19], v[16:17], off
	v_mfma_f32_16x16x32_bf16 v[16:19], v[68:71], v[12:15], 0
	v_lshlrev_b32_e32 v20, 16, v124
	v_mul_f32_e32 v21, 0xbfb8aa3b, v20
	v_exp_f32_e32 v21, v21
	v_mfma_f32_16x16x32_bf16 v[16:19], v[64:67], v[8:11], v[16:19]
	v_lshlrev_b32_e32 v24, 16, v125
	v_and_b32_e32 v26, 0xffff0000, v125
	v_add_f32_e32 v21, 1.0, v21
	v_mfma_f32_16x16x32_bf16 v[12:15], v[48:51], v[12:15], 0
	v_rcp_f32_e32 v28, v21
	s_add_u32 s0, s9, s5
	s_addc_u32 s1, s8, s10
	v_mfma_f32_16x16x32_bf16 v[16:19], v[60:63], v[4:7], v[16:19]
	s_lshl_b64 s[0:1], s[0:1], 10
	s_add_u32 s0, s6, s0
	s_addc_u32 s1, s7, s1
	v_mfma_f32_16x16x32_bf16 v[8:11], v[44:47], v[8:11], v[12:15]
	s_cmp_lg_u32 s4, 0
	v_mfma_f32_16x16x32_bf16 v[16:19], v[56:59], v[0:3], v[16:19]
	s_nop 0
	v_mov_b32_e32 v13, v32
	v_mfma_f32_16x16x32_bf16 v[4:7], v[40:43], v[4:7], v[8:11]
	v_mfma_f32_16x16x32_bf16 v[0:3], v[36:39], v[0:3], v[4:7]
	s_nop 3
	v_mov_b32_e32 v21, v16
	v_mul_f32_e32 v16, 0xbfb8aa3b, v22
	v_exp_f32_e32 v16, v16
	s_waitcnt vmcnt(6)
	v_lshlrev_b32_e32 v4, 16, v118
	v_mul_f32_e32 v5, 0xbfb8aa3b, v4
	v_exp_f32_e32 v5, v5
	v_add_f32_e32 v16, 1.0, v16
	v_rcp_f32_e32 v52, v16
	v_and_b32_e32 v6, 0xffff0000, v118
	v_add_f32_e32 v5, 1.0, v5
	v_rcp_f32_e32 v12, v5
	v_mov_b32_e32 v5, v0
	v_mul_f32_e32 v0, 0xbfb8aa3b, v6
	v_mov_b32_e32 v23, v17
	v_exp_f32_e32 v0, v0
	v_pk_mul_f32 v[16:17], v[52:53], v[22:23]
	v_mov_b32_e32 v25, v18
	v_mul_f32_e32 v16, v16, v17
	v_mul_f32_e32 v17, 0xbfb8aa3b, v24
	v_mul_f32_e32 v18, 0xbfb8aa3b, v26
	v_exp_f32_e32 v17, v17
	v_exp_f32_e32 v18, v18
	v_add_f32_e32 v0, 1.0, v0
	v_rcp_f32_e32 v32, v0
	v_pk_mul_f32 v[20:21], v[28:29], v[20:21]
	v_add_f32_e32 v17, 1.0, v17
	v_mul_f32_e32 v20, v20, v21
	v_add_f32_e32 v18, 1.0, v18
	v_cvt_pk_bf16_f32 v16, v20, v16
	v_rcp_f32_e32 v20, v17
	v_mov_b32_e32 v21, v54
	v_rcp_f32_e32 v54, v18
	v_mov_b32_e32 v7, v1
	v_lshlrev_b32_e32 v8, 16, v119
	v_and_b32_e32 v10, 0xffff0000, v119
	v_pk_mul_f32 v[0:1], v[32:33], v[6:7]
	v_mov_b32_e32 v9, v2
	v_mul_f32_e32 v0, v0, v1
	v_mul_f32_e32 v1, 0xbfb8aa3b, v8
	v_mul_f32_e32 v2, 0xbfb8aa3b, v10
	v_mov_b32_e32 v27, v19
	v_exp_f32_e32 v1, v1
	v_exp_f32_e32 v2, v2
	v_pk_mul_f32 v[20:21], v[20:21], v[24:25]
	v_pk_mul_f32 v[18:19], v[54:55], v[26:27]
	v_mul_f32_e32 v17, v20, v21
	v_mul_f32_e32 v18, v18, v19
	v_cvt_pk_bf16_f32 v17, v17, v18
	v_lshl_add_u64 v[18:19], s[0:1], 0, v[112:113]
	v_pk_mul_f32 v[4:5], v[12:13], v[4:5]
	v_lshl_add_u64 v[18:19], v[18:19], 0, v[184:185]
	v_mul_f32_e32 v4, v4, v5
	v_add_f32_e32 v1, 1.0, v1
	v_add_f32_e32 v2, 1.0, v2
	global_store_dwordx2 v[18:19], v[16:17], off
	v_cvt_pk_bf16_f32 v0, v4, v0
	v_rcp_f32_e32 v4, v1
	v_mov_b32_e32 v5, v34
	v_rcp_f32_e32 v34, v2
	v_mov_b32_e32 v11, v3
	v_pk_mul_f32 v[4:5], v[4:5], v[8:9]
	v_pk_mul_f32 v[2:3], v[34:35], v[10:11]
	v_mul_f32_e32 v1, v4, v5
	v_mul_f32_e32 v2, v2, v3
	v_cvt_pk_bf16_f32 v1, v1, v2
	v_lshl_add_u64 v[2:3], s[0:1], 0, v[114:115]
	v_lshl_add_u64 v[2:3], v[2:3], 0, v[184:185]
	global_store_dwordx2 v[2:3], v[0:1], off
	v_cvt_f32_i32_e32 v0, s42
	s_mov_b64 s[0:1], -1
	s_barrier
	v_sub_f32_e32 v221, 0xc0a00000, v0
	s_cbranch_scc0 .LBB0_788
	v_cmp_gt_f32_e32 vcc, s75, v221
	s_bfe_u32 s4, s16, 0x40004
	s_and_b64 s[0:1], vcc, exec
	v_cndmask_b32_e32 v0, 0, v231, vcc
	v_add_f32_e32 v0, v221, v0
	v_exp_f32_e32 v0, v0
	s_cselect_b32 s0, 0xffffffc0, 0
	s_mov_b64 s[20:21], s[64:65]
	v_mov_b32_e32 v187, v197
	v_ldexp_f32 v0, v0, s0
	s_lshl_b32 s0, s42, 2
	s_add_i32 s0, s12, s0
	v_sub_f32_e32 v120, 1.0, v0
	v_lshl_add_u64 v[0:1], s[20:21], 0, v[186:187]
	s_mov_b64 s[6:7], 0x1a801000
	s_ashr_i32 s1, s0, 31
	v_lshl_add_u64 v[0:1], v[0:1], 0, s[6:7]
	s_lshl_b64 s[6:7], s[0:1], 10
	s_add_i32 s0, s0, 16
	s_ashr_i32 s1, s0, 31
	s_lshl_b64 s[0:1], s[0:1], 10
	s_ashr_i32 s5, s69, 4
	s_ashr_i32 s19, s18, 31
	v_lshl_add_u64 v[2:3], v[0:1], 0, s[6:7]
	v_lshl_add_u64 v[0:1], v[0:1], 0, s[0:1]
	s_add_u32 s0, s20, 0xee01000
	s_addc_u32 s1, s21, 0
	s_lshl_b32 s7, s4, 13
	s_lshl_b32 s8, s5, 17
	s_lshl_b32 s6, s42, 11
	s_or_b32 s7, s7, s8
	s_add_i32 s6, s7, s6
	s_ashr_i32 s7, s6, 31
	global_load_dwordx4 v[44:47], v[2:3], off nt
	global_load_dwordx4 v[48:51], v[2:3], off offset:1024 nt
	global_load_dwordx4 v[52:55], v[2:3], off offset:2048 nt
	global_load_dwordx4 v[56:59], v[2:3], off offset:3072 nt
	global_load_dwordx4 v[32:35], v[0:1], off nt
	global_load_dwordx4 v[20:23], v[0:1], off offset:1024 nt
	global_load_dwordx4 v[24:27], v[0:1], off offset:2048 nt
	global_load_dwordx4 v[28:31], v[0:1], off offset:3072 nt
	v_mov_b32_e32 v1, s7
	s_or_b32 s7, s6, 0x100
	s_ashr_i32 s8, s7, 31
	v_or_b32_e32 v0, s6, v220
	v_or_b32_e32 v16, s7, v220
	v_mov_b32_e32 v17, s8
	v_lshl_add_u64 v[12:13], v[0:1], 4, s[0:1]
	v_lshl_add_u64 v[60:61], v[16:17], 4, s[0:1]
	global_load_dwordx4 v[0:3], v[12:13], off
	global_load_dwordx4 v[4:7], v[12:13], off offset:1024
	global_load_dwordx4 v[8:11], v[12:13], off offset:2048
	s_nop 0
	global_load_dwordx4 v[12:15], v[12:13], off offset:3072
	s_nop 0
	global_load_dwordx4 v[16:19], v[60:61], off
	global_load_dwordx4 v[36:39], v[60:61], off offset:1024
	global_load_dwordx4 v[40:43], v[60:61], off offset:2048
	s_nop 0
	global_load_dwordx4 v[60:63], v[60:61], off offset:3072
	v_or_b32_e32 v239, 32, v208
	s_waitcnt vmcnt(7)
	v_mfma_f32_16x16x32_bf16 v[64:67], v[0:3], v[44:47], 0
	s_or_b32 s7, s6, 0x200
	s_ashr_i32 s8, s7, 31
	v_mfma_f32_16x16x32_bf16 v[0:3], v[0:3], v[32:35], 0
	s_waitcnt vmcnt(6)
	v_mfma_f32_16x16x32_bf16 v[64:67], v[4:7], v[48:51], v[64:67]
	v_mfma_f32_16x16x32_bf16 v[0:3], v[4:7], v[20:23], v[0:3]
	s_waitcnt vmcnt(5)
	v_mfma_f32_16x16x32_bf16 v[4:7], v[8:11], v[52:55], v[64:67]
	v_mfma_f32_16x16x32_bf16 v[0:3], v[8:11], v[24:27], v[0:3]
	s_waitcnt vmcnt(4)
	v_mfma_f32_16x16x32_bf16 v[8:11], v[12:15], v[56:59], v[4:7]
	v_mfma_f32_16x16x32_bf16 v[0:3], v[12:15], v[28:31], v[0:3]
	s_waitcnt vmcnt(3)
	v_mfma_f32_16x16x32_bf16 v[4:7], v[16:19], v[44:47], 0
	v_mfma_f32_16x16x32_bf16 v[12:15], v[16:19], v[32:35], 0
	s_waitcnt vmcnt(2)
	v_mfma_f32_16x16x32_bf16 v[4:7], v[36:39], v[48:51], v[4:7]
	v_mfma_f32_16x16x32_bf16 v[12:15], v[36:39], v[20:23], v[12:15]
	s_waitcnt vmcnt(1)
	v_mfma_f32_16x16x32_bf16 v[4:7], v[40:43], v[52:55], v[4:7]
	v_mfma_f32_16x16x32_bf16 v[16:19], v[40:43], v[24:27], v[12:15]
	s_waitcnt vmcnt(0)
	v_mfma_f32_16x16x32_bf16 v[12:15], v[60:63], v[56:59], v[4:7]
	v_mfma_f32_16x16x32_bf16 v[4:7], v[60:63], v[28:31], v[16:19]
	s_nop 4
	v_or_b32_e32 v16, s7, v220
	s_or_b32 s7, s6, 0x300
	v_mov_b32_e32 v17, s8
	s_ashr_i32 s8, s7, 31
	v_or_b32_e32 v64, s7, v220
	v_mov_b32_e32 v65, s8
	v_lshl_add_u64 v[60:61], v[16:17], 4, s[0:1]
	v_lshl_add_u64 v[76:77], v[64:65], 4, s[0:1]
	global_load_dwordx4 v[16:19], v[60:61], off
	global_load_dwordx4 v[36:39], v[60:61], off offset:1024
	global_load_dwordx4 v[40:43], v[60:61], off offset:2048
	s_nop 0
	global_load_dwordx4 v[60:63], v[60:61], off offset:3072
	s_nop 0
	global_load_dwordx4 v[64:67], v[76:77], off
	global_load_dwordx4 v[68:71], v[76:77], off offset:1024
	global_load_dwordx4 v[72:75], v[76:77], off offset:2048
	s_nop 0
	global_load_dwordx4 v[76:79], v[76:77], off offset:3072
	s_waitcnt vmcnt(7)
	v_mfma_f32_16x16x32_bf16 v[80:83], v[16:19], v[44:47], 0
	s_or_b32 s7, s6, 0x400
	s_ashr_i32 s8, s7, 31
	v_mfma_f32_16x16x32_bf16 v[16:19], v[16:19], v[32:35], 0
	s_waitcnt vmcnt(6)
	v_mfma_f32_16x16x32_bf16 v[80:83], v[36:39], v[48:51], v[80:83]
	v_mfma_f32_16x16x32_bf16 v[16:19], v[36:39], v[20:23], v[16:19]
	s_waitcnt vmcnt(5)
	v_mfma_f32_16x16x32_bf16 v[36:39], v[40:43], v[52:55], v[80:83]
	v_mfma_f32_16x16x32_bf16 v[16:19], v[40:43], v[24:27], v[16:19]
	s_waitcnt vmcnt(4)
	v_mfma_f32_16x16x32_bf16 v[40:43], v[60:63], v[56:59], v[36:39]
	v_mfma_f32_16x16x32_bf16 v[16:19], v[60:63], v[28:31], v[16:19]
	s_waitcnt vmcnt(3)
	v_mfma_f32_16x16x32_bf16 v[36:39], v[64:67], v[44:47], 0
	v_mfma_f32_16x16x32_bf16 v[60:63], v[64:67], v[32:35], 0
	s_waitcnt vmcnt(2)
	v_mfma_f32_16x16x32_bf16 v[36:39], v[68:71], v[48:51], v[36:39]
	v_mfma_f32_16x16x32_bf16 v[60:63], v[68:71], v[20:23], v[60:63]
	s_waitcnt vmcnt(1)
	v_mfma_f32_16x16x32_bf16 v[36:39], v[72:75], v[52:55], v[36:39]
	v_mfma_f32_16x16x32_bf16 v[64:67], v[72:75], v[24:27], v[60:63]
	s_waitcnt vmcnt(0)
	v_mfma_f32_16x16x32_bf16 v[60:63], v[76:79], v[56:59], v[36:39]
	v_mfma_f32_16x16x32_bf16 v[36:39], v[76:79], v[28:31], v[64:67]
	s_nop 4
	v_or_b32_e32 v64, s7, v220
	s_or_b32 s7, s6, 0x500
	v_mov_b32_e32 v65, s8
	s_ashr_i32 s8, s7, 31
	v_or_b32_e32 v80, s7, v220
	v_mov_b32_e32 v81, s8
	v_lshl_add_u64 v[76:77], v[64:65], 4, s[0:1]
	v_lshl_add_u64 v[92:93], v[80:81], 4, s[0:1]
	global_load_dwordx4 v[64:67], v[76:77], off
	global_load_dwordx4 v[68:71], v[76:77], off offset:1024
	global_load_dwordx4 v[72:75], v[76:77], off offset:2048
	s_nop 0
	global_load_dwordx4 v[76:79], v[76:77], off offset:3072
	s_nop 0
	global_load_dwordx4 v[80:83], v[92:93], off
	global_load_dwordx4 v[84:87], v[92:93], off offset:1024
	global_load_dwordx4 v[88:91], v[92:93], off offset:2048
	s_nop 0
	global_load_dwordx4 v[92:95], v[92:93], off offset:3072
	s_waitcnt vmcnt(7)
	v_mfma_f32_16x16x32_bf16 v[96:99], v[64:67], v[44:47], 0
	s_or_b32 s7, s6, 0x600
	s_or_b32 s6, s6, 0x700
	s_ashr_i32 s8, s7, 31
	v_mfma_f32_16x16x32_bf16 v[64:67], v[64:67], v[32:35], 0
	s_waitcnt vmcnt(6)
	v_mfma_f32_16x16x32_bf16 v[64:67], v[68:71], v[20:23], v[64:67]
	v_mfma_f32_16x16x32_bf16 v[96:99], v[68:71], v[48:51], v[96:99]
	s_waitcnt vmcnt(5)
	v_mfma_f32_16x16x32_bf16 v[64:67], v[72:75], v[24:27], v[64:67]
	v_mfma_f32_16x16x32_bf16 v[68:71], v[72:75], v[52:55], v[96:99]
	s_waitcnt vmcnt(4)
	v_mfma_f32_16x16x32_bf16 v[100:103], v[76:79], v[28:31], v[64:67]
	s_waitcnt vmcnt(3)
	v_mfma_f32_16x16x32_bf16 v[64:67], v[80:83], v[44:47], 0
	v_mfma_f32_16x16x32_bf16 v[96:99], v[76:79], v[56:59], v[68:71]
	v_mfma_f32_16x16x32_bf16 v[68:71], v[80:83], v[32:35], 0
	v_or_b32_e32 v80, s6, v220
	s_waitcnt vmcnt(2)
	v_mfma_f32_16x16x32_bf16 v[64:67], v[84:87], v[48:51], v[64:67]
	v_mfma_f32_16x16x32_bf16 v[68:71], v[84:87], v[20:23], v[68:71]
	s_waitcnt vmcnt(1)
	v_mfma_f32_16x16x32_bf16 v[64:67], v[88:91], v[52:55], v[64:67]
	v_mfma_f32_16x16x32_bf16 v[68:71], v[88:91], v[24:27], v[68:71]
	s_waitcnt vmcnt(0)
	v_mfma_f32_16x16x32_bf16 v[84:87], v[92:95], v[56:59], v[64:67]
	s_nop 4
	v_or_b32_e32 v64, s7, v220
	s_ashr_i32 s7, s6, 31
	v_mov_b32_e32 v65, s8
	v_mov_b32_e32 v81, s7
	v_lshl_add_u64 v[76:77], v[64:65], 4, s[0:1]
	v_lshl_add_u64 v[108:109], v[80:81], 4, s[0:1]
	v_mfma_f32_16x16x32_bf16 v[104:107], v[92:95], v[28:31], v[68:71]
	global_load_dwordx4 v[64:67], v[76:77], off
	s_nop 1
	global_load_dwordx4 v[68:71], v[76:77], off offset:1024
	global_load_dwordx4 v[72:75], v[76:77], off offset:2048
	s_nop 0
	global_load_dwordx4 v[76:79], v[76:77], off offset:3072
	s_nop 0
	global_load_dwordx4 v[80:83], v[108:109], off
	global_load_dwordx4 v[88:91], v[108:109], off offset:1024
	global_load_dwordx4 v[92:95], v[108:109], off offset:2048
	s_nop 0
	global_load_dwordx4 v[108:111], v[108:109], off offset:3072
	s_waitcnt vmcnt(7)
	v_mfma_f32_16x16x32_bf16 v[112:115], v[64:67], v[44:47], 0
	v_cmp_gt_f32_e32 vcc, s15, v120
	s_and_b64 s[0:1], vcc, exec
	s_cselect_b32 s0, 32, 0
	v_mfma_f32_16x16x32_bf16 v[64:67], v[64:67], v[32:35], 0
	s_or_b32 s6, s68, 64
	s_lshl_b32 s1, s42, 4
	s_ashr_i32 s43, s42, 31
	s_waitcnt vmcnt(6)
	v_mfma_f32_16x16x32_bf16 v[64:67], v[68:71], v[20:23], v[64:67]
	s_lshl_b64 s[10:11], s[42:43], 12
	v_mov_b32_e32 v189, v197
	v_mfma_f32_16x16x32_bf16 v[112:115], v[68:71], v[48:51], v[112:115]
	s_waitcnt vmcnt(5)
	v_mfma_f32_16x16x32_bf16 v[64:67], v[72:75], v[24:27], v[64:67]
	v_mfma_f32_16x16x32_bf16 v[68:71], v[72:75], v[52:55], v[112:115]
	s_waitcnt vmcnt(4)
	v_mfma_f32_16x16x32_bf16 v[116:119], v[76:79], v[28:31], v[64:67]
	s_waitcnt vmcnt(3)
	v_mfma_f32_16x16x32_bf16 v[64:67], v[80:83], v[44:47], 0
	v_mfma_f32_16x16x32_bf16 v[112:115], v[76:79], v[56:59], v[68:71]
	v_mfma_f32_16x16x32_bf16 v[68:71], v[80:83], v[32:35], 0
	s_waitcnt vmcnt(2)
	v_mfma_f32_16x16x32_bf16 v[64:67], v[88:91], v[48:51], v[64:67]
	v_mfma_f32_16x16x32_bf16 v[68:71], v[88:91], v[20:23], v[68:71]
	s_waitcnt vmcnt(1)
	v_mfma_f32_16x16x32_bf16 v[64:67], v[92:95], v[52:55], v[64:67]
	v_mfma_f32_16x16x32_bf16 v[68:71], v[92:95], v[24:27], v[68:71]
	s_waitcnt vmcnt(0)
	v_mfma_f32_16x16x32_bf16 v[92:95], v[108:111], v[56:59], v[64:67]
	s_nop 4
	v_ldexp_f32 v64, v120, s0
	v_log_f32_e32 v64, v64
	v_cndmask_b32_e32 v65, 0, v232, vcc
	s_lshl_b32 s0, s5, 6
	s_add_i32 s1, s1, s0
	v_sub_f32_e32 v185, v64, v65
	v_add3_u32 v64, v206, s6, 1
	v_cvt_f32_u32_e32 v64, v64
	s_or_b32 s0, s1, s4
	v_lshl_or_b32 v190, s0, 9, v206
	s_lshl_b64 s[0:1], s[18:19], 10
	v_mul_f32_e32 v64, v185, v64
	v_exp_f32_e32 v120, v64
	s_add_u32 s0, s20, s0
	s_addc_u32 s1, s21, s1
	s_add_u32 s0, s0, 0x1b801000
	v_pk_mul_f32 v[64:65], v[120:121], v[8:9] op_sel_hi:[0,1]
	v_add_u32_e32 v8, s68, v206
	v_add_u32_e32 v8, 0x51, v8
	v_cvt_f32_ubyte0_e32 v8, v8
	v_mul_f32_e32 v8, v185, v8
	s_addc_u32 s1, s1, 0
	v_mfma_f32_16x16x32_bf16 v[108:111], v[108:111], v[28:31], v[68:71]
	v_mul_f32_e64 v76, v120, v60
	v_mul_f32_e64 v77, v120, v61
	v_exp_f32_e32 v60, v8
	s_add_u32 s4, s0, s10
	s_addc_u32 s5, s1, s11
	v_lshl_add_u64 v[204:205], s[4:5], 0, v[186:187]
	v_pk_mul_f32 v[82:83], v[120:121], v[98:99] op_sel_hi:[0,1]
	v_add_co_u32_e32 v98, vcc, s71, v204
	v_pk_mul_f32 v[66:67], v[120:121], v[10:11] op_sel_hi:[0,1]
	v_pk_mul_f32 v[70:71], v[120:121], v[14:15] op_sel_hi:[0,1]
	v_pk_mul_f32 v[68:69], v[120:121], v[12:13] op_sel_hi:[0,1]
	v_pk_mul_f32 v[74:75], v[120:121], v[42:43] op_sel_hi:[0,1]
	v_pk_mul_f32 v[72:73], v[120:121], v[40:41] op_sel_hi:[0,1]
	v_pk_mul_f32 v[78:79], v[120:121], v[62:63] op_sel_hi:[0,1]
	v_pk_mul_f32 v[80:81], v[120:121], v[96:97] op_sel_hi:[0,1]
	v_pk_mul_f32 v[88:89], v[120:121], v[112:113] op_sel_hi:[0,1]
	v_pk_mul_f32 v[2:3], v[60:61], v[2:3] op_sel_hi:[0,1]
	v_pk_mul_f32 v[0:1], v[60:61], v[0:1] op_sel_hi:[0,1]
	v_pk_mul_f32 v[6:7], v[60:61], v[6:7] op_sel_hi:[0,1]
	v_pk_mul_f32 v[4:5], v[60:61], v[4:5] op_sel_hi:[0,1]
	v_pk_mul_f32 v[10:11], v[60:61], v[18:19] op_sel_hi:[0,1]
	v_pk_mul_f32 v[8:9], v[60:61], v[16:17] op_sel_hi:[0,1]
	v_pk_mul_f32 v[14:15], v[60:61], v[38:39] op_sel_hi:[0,1]
	v_pk_mul_f32 v[12:13], v[60:61], v[36:37] op_sel_hi:[0,1]
	v_pk_mul_f32 v[18:19], v[60:61], v[102:103] op_sel_hi:[0,1]
	v_pk_mul_f32 v[16:17], v[60:61], v[100:101] op_sel_hi:[0,1]
	v_pk_mul_f32 v[38:39], v[60:61], v[106:107] op_sel_hi:[0,1]
	v_pk_mul_f32 v[36:37], v[60:61], v[104:105] op_sel_hi:[0,1]
	v_pk_mul_f32 v[42:43], v[60:61], v[118:119] op_sel_hi:[0,1]
	v_pk_mul_f32 v[40:41], v[60:61], v[116:117] op_sel_hi:[0,1]
	v_pk_mul_f32 v[62:63], v[60:61], v[110:111] op_sel_hi:[0,1]
	v_pk_mul_f32 v[60:61], v[60:61], v[108:109] op_sel_hi:[0,1]
	v_lshl_add_u64 v[96:97], s[20:21], 0, v[188:189]
	global_load_dwordx4 v[144:147], v186, s[4:5]
	global_load_dwordx4 v[148:151], v186, s[4:5] offset:1024
	global_load_dwordx4 v[152:155], v186, s[4:5] offset:2048
	global_load_dwordx4 v[156:159], v186, s[4:5] offset:3072
	s_mov_b64 s[4:5], 0x4000
	v_addc_co_u32_e32 v99, vcc, 0, v205, vcc
	v_or_b32_e32 v100, 16, v190
	v_or_b32_e32 v104, 32, v190
	v_or_b32_e32 v108, 48, v190
	v_or_b32_e32 v112, 64, v190
	v_or_b32_e32 v124, 0x50, v190
	v_or_b32_e32 v132, 0x60, v190
	v_or_b32_e32 v140, 0x70, v190
	v_pk_mul_f32 v[86:87], v[120:121], v[86:87] op_sel_hi:[0,1]
	v_pk_mul_f32 v[84:85], v[120:121], v[84:85] op_sel_hi:[0,1]
	v_pk_mul_f32 v[90:91], v[120:121], v[114:115] op_sel_hi:[0,1]
	v_pk_mul_f32 v[94:95], v[120:121], v[94:95] op_sel_hi:[0,1]
	v_pk_mul_f32 v[92:93], v[120:121], v[92:93] op_sel_hi:[0,1]
	v_lshl_add_u64 v[202:203], v[96:97], 0, s[58:59]
	v_lshl_add_u64 v[96:97], v[204:205], 0, s[4:5]
	global_load_dwordx4 v[136:139], v[98:99], off
	global_load_dwordx4 v[128:131], v[96:97], off offset:1024
	global_load_dwordx4 v[116:119], v[96:97], off offset:2048
	global_load_dwordx4 v[120:123], v[96:97], off offset:3072
	v_ashrrev_i32_e32 v191, 31, v190
	v_ashrrev_i32_e32 v101, 31, v100
	v_ashrrev_i32_e32 v105, 31, v104
	v_ashrrev_i32_e32 v109, 31, v108
	v_ashrrev_i32_e32 v113, 31, v112
	v_ashrrev_i32_e32 v125, 31, v124
	v_ashrrev_i32_e32 v133, 31, v132
	v_ashrrev_i32_e32 v141, 31, v140
	v_lshlrev_b64 v[96:97], 6, v[190:191]
	v_lshlrev_b64 v[100:101], 6, v[100:101]
	v_lshlrev_b64 v[104:105], 6, v[104:105]
	v_lshlrev_b64 v[108:109], 6, v[108:109]
	v_lshlrev_b64 v[112:113], 6, v[112:113]
	v_lshlrev_b64 v[124:125], 6, v[124:125]
	v_lshlrev_b64 v[132:133], 6, v[132:133]
	v_lshlrev_b64 v[140:141], 6, v[140:141]
	v_lshl_add_u64 v[96:97], v[202:203], 0, v[96:97]
	v_lshl_add_u64 v[100:101], v[202:203], 0, v[100:101]
	v_lshl_add_u64 v[104:105], v[202:203], 0, v[104:105]
	v_lshl_add_u64 v[108:109], v[202:203], 0, v[108:109]
	v_lshl_add_u64 v[112:113], v[202:203], 0, v[112:113]
	v_lshl_add_u64 v[124:125], v[202:203], 0, v[124:125]
	v_lshl_add_u64 v[132:133], v[202:203], 0, v[132:133]
	v_lshl_add_u64 v[140:141], v[202:203], 0, v[140:141]
	global_load_dwordx4 v[96:99], v[96:97], off
	s_nop 0
	global_load_dwordx4 v[100:103], v[100:101], off
	s_nop 0
	global_load_dwordx4 v[104:107], v[104:105], off
	s_nop 0
	global_load_dwordx4 v[108:111], v[108:109], off
	s_nop 0
	global_load_dwordx4 v[112:115], v[112:113], off
	s_nop 0
	global_load_dwordx4 v[124:127], v[124:125], off
	s_nop 0
	global_load_dwordx4 v[132:135], v[132:133], off
	s_nop 0
	global_load_dwordx4 v[140:143], v[140:141], off
	s_waitcnt vmcnt(15)
	v_mfma_f32_16x16x32_bf16 v[160:163], v[144:147], v[44:47], 0
	v_or_b32_e32 v191, s6, v206
	v_sub_u32_e32 v164, v191, v208
	v_cvt_f32_ubyte0_e32 v164, v164
	s_waitcnt vmcnt(14)
	v_mfma_f32_16x16x32_bf16 v[160:163], v[148:151], v[48:51], v[160:163]
	v_mul_f32_e32 v164, v185, v164
	v_exp_f32_e32 v164, v164
	v_or_b32_e32 v189, 0x50, v212
	s_waitcnt vmcnt(13)
	v_mfma_f32_16x16x32_bf16 v[160:163], v[152:155], v[52:55], v[160:163]
	v_sub_u32_e32 v166, v191, v213
	v_cvt_f32_ubyte0_e32 v166, v166
	v_mul_f32_e32 v166, v185, v166
	s_waitcnt vmcnt(12)
	v_mfma_f32_16x16x32_bf16 v[160:163], v[156:159], v[56:59], v[160:163]
	v_exp_f32_e32 v166, v166
	s_mov_b64 s[4:5], 0x8000
	v_mfma_f32_16x16x32_bf16 v[144:147], v[144:147], v[32:35], 0
	v_mfma_f32_16x16x32_bf16 v[144:147], v[148:151], v[20:23], v[144:147]
	s_nop 3
	v_mul_f32_e32 v160, v164, v160
	v_add_u32_e32 v164, v191, v219
	v_cvt_f32_ubyte0_e32 v164, v164
	v_mul_f32_e32 v164, v185, v164
	v_exp_f32_e32 v164, v164
	v_mfma_f32_16x16x32_bf16 v[144:147], v[152:155], v[24:27], v[144:147]
	v_sub_u32_e32 v148, v189, v208
	v_cvt_f32_ubyte0_e32 v148, v148
	v_mul_f32_e32 v161, v164, v161
	v_sub_u32_e32 v164, v191, v218
	v_cvt_f32_ubyte0_e32 v164, v164
	v_mul_f32_e32 v164, v185, v164
	v_exp_f32_e32 v164, v164
	v_cvt_pk_bf16_f32 v160, v160, v161
	v_mul_f32_e32 v148, v185, v148
	v_mfma_f32_16x16x32_bf16 v[144:147], v[156:159], v[28:31], v[144:147]
	v_mul_f32_e32 v162, v164, v162
	v_sub_u32_e32 v164, v191, v217
	v_cvt_f32_ubyte0_e32 v164, v164
	v_mul_f32_e32 v164, v185, v164
	v_exp_f32_e32 v164, v164
	v_exp_f32_e32 v148, v148
	v_mul_f32_e32 v163, v164, v163
	v_cvt_pk_bf16_f32 v161, v162, v163
	s_waitcnt vmcnt(11)
	v_mfma_f32_16x16x32_bf16 v[162:165], v[136:139], v[44:47], 0
	v_mul_f32_e32 v144, v148, v144
	v_add_u32_e32 v148, v189, v219
	v_cvt_f32_ubyte0_e32 v148, v148
	v_mfma_f32_16x16x32_bf16 v[136:139], v[136:139], v[32:35], 0
	v_mul_f32_e32 v148, v185, v148
	v_exp_f32_e32 v148, v148
	s_waitcnt vmcnt(10)
	v_mfma_f32_16x16x32_bf16 v[162:165], v[128:131], v[48:51], v[162:165]
	v_mul_f32_e32 v145, v148, v145
	v_sub_u32_e32 v148, v189, v218
	v_mfma_f32_16x16x32_bf16 v[128:131], v[128:131], v[20:23], v[136:139]
	v_cvt_f32_ubyte0_e32 v148, v148
	v_mul_f32_e32 v148, v185, v148
	v_exp_f32_e32 v148, v148
	s_waitcnt vmcnt(9)
	v_mfma_f32_16x16x32_bf16 v[162:165], v[116:119], v[52:55], v[162:165]
	v_mul_f32_e32 v146, v148, v146
	v_mfma_f32_16x16x32_bf16 v[116:119], v[116:119], v[24:27], v[128:131]
	v_sub_u32_e32 v148, v189, v217
	v_cvt_f32_ubyte0_e32 v148, v148
	v_mul_f32_e32 v148, v185, v148
	s_waitcnt vmcnt(8)
	v_mfma_f32_16x16x32_bf16 v[162:165], v[120:123], v[56:59], v[162:165]
	v_exp_f32_e32 v148, v148
	s_nop 0
	v_mul_f32_e32 v147, v148, v147
	v_mfma_f32_16x16x32_bf16 v[116:119], v[120:123], v[28:31], v[116:119]
	v_sub_u32_e32 v120, v189, v213
	v_cvt_f32_ubyte0_e32 v120, v120
	v_mul_f32_e32 v120, v185, v120
	v_exp_f32_e32 v120, v120
	v_mul_f32_e32 v162, v166, v162
	v_sub_u32_e32 v166, v191, v216
	v_cvt_f32_ubyte0_e32 v166, v166
	s_nop 0
	v_mul_f32_e32 v116, v120, v116
	v_sub_u32_e32 v120, v189, v216
	v_cvt_f32_ubyte0_e32 v120, v120
	v_mul_f32_e32 v166, v185, v166
	v_mul_f32_e32 v120, v185, v120
	v_exp_f32_e32 v166, v166
	v_exp_f32_e32 v120, v120
	v_mul_f32_e32 v163, v166, v163
	v_sub_u32_e32 v166, v191, v215
	v_mul_f32_e32 v117, v120, v117
	v_sub_u32_e32 v120, v189, v215
	v_cvt_f32_ubyte0_e32 v166, v166
	v_cvt_f32_ubyte0_e32 v120, v120
	v_mul_f32_e32 v166, v185, v166
	v_mul_f32_e32 v120, v185, v120
	v_exp_f32_e32 v166, v166
	v_exp_f32_e32 v120, v120
	v_cvt_pk_bf16_f32 v162, v162, v163
	v_mul_f32_e32 v164, v166, v164
	v_sub_u32_e32 v166, v191, v214
	v_mul_f32_e32 v118, v120, v118
	v_sub_u32_e32 v120, v189, v214
	v_cvt_f32_ubyte0_e32 v166, v166
	v_cvt_f32_ubyte0_e32 v120, v120
	v_mul_f32_e32 v166, v185, v166
	v_mul_f32_e32 v120, v185, v120
	v_exp_f32_e32 v166, v166
	v_exp_f32_e32 v120, v120
	v_mul_f32_e32 v165, v166, v165
	v_cvt_pk_bf16_f32 v163, v164, v165
	v_cvt_pk_bf16_f32 v144, v144, v145
	v_cvt_pk_bf16_f32 v145, v146, v147
	v_mul_f32_e32 v119, v120, v119
	s_waitcnt vmcnt(7)
	v_mfma_f32_16x16x32_bf16 v[64:67], v[96:99], v[160:163], v[64:67]
	v_cvt_pk_bf16_f32 v146, v116, v117
	v_cvt_pk_bf16_f32 v147, v118, v119
	s_nop 0
	v_mfma_f32_16x16x32_bf16 v[0:3], v[96:99], v[144:147], v[0:3]
	s_waitcnt vmcnt(3)
	v_mfma_f32_16x16x32_bf16 v[96:99], v[112:115], v[144:147], v[16:19]
	s_nop 2
	v_add_co_u32_e32 v18, vcc, s73, v204
	v_lshl_add_u64 v[16:17], v[204:205], 0, s[4:5]
	s_nop 0
	v_addc_co_u32_e32 v19, vcc, 0, v205, vcc
	s_mov_b64 s[4:5], 0xc000
	global_load_dwordx4 v[168:171], v[18:19], off
	global_load_dwordx4 v[172:175], v[16:17], off offset:1024
	global_load_dwordx4 v[176:179], v[16:17], off offset:2048
	global_load_dwordx4 v[180:183], v[16:17], off offset:3072
	v_lshl_add_u64 v[16:17], v[204:205], 0, s[4:5]
	s_mov_b32 s4, 0xc000
	v_add_co_u32_e32 v18, vcc, s4, v204
	v_mfma_f32_16x16x32_bf16 v[76:79], v[108:111], v[160:163], v[76:79]
	s_nop 0
	v_addc_co_u32_e32 v19, vcc, 0, v205, vcc
	s_waitcnt vmcnt(4)
	v_mfma_f32_16x16x32_bf16 v[92:95], v[140:143], v[160:163], v[92:95]
	v_mfma_f32_16x16x32_bf16 v[12:15], v[108:111], v[144:147], v[12:15]
	v_mfma_f32_16x16x32_bf16 v[108:111], v[140:143], v[144:147], v[60:63]
	global_load_dwordx4 v[164:167], v[18:19], off
	global_load_dwordx4 v[156:159], v[16:17], off offset:1024
	global_load_dwordx4 v[148:151], v[16:17], off offset:2048
	global_load_dwordx4 v[140:143], v[16:17], off offset:3072
	v_or_b32_e32 v16, 0x80, v190
	v_ashrrev_i32_e32 v17, 31, v16
	v_lshlrev_b64 v[16:17], 6, v[16:17]
	v_lshl_add_u64 v[16:17], v[202:203], 0, v[16:17]
	global_load_dwordx4 v[120:123], v[16:17], off
	v_or_b32_e32 v16, 0x90, v190
	v_ashrrev_i32_e32 v17, 31, v16
	v_lshlrev_b64 v[16:17], 6, v[16:17]
	v_lshl_add_u64 v[16:17], v[202:203], 0, v[16:17]
	v_mfma_f32_16x16x32_bf16 v[68:71], v[100:103], v[160:163], v[68:71]
	v_mfma_f32_16x16x32_bf16 v[84:87], v[124:127], v[160:163], v[84:87]
	v_mfma_f32_16x16x32_bf16 v[4:7], v[100:103], v[144:147], v[4:7]
	v_mfma_f32_16x16x32_bf16 v[100:103], v[124:127], v[144:147], v[36:39]
	global_load_dwordx4 v[124:127], v[16:17], off
	v_or_b32_e32 v16, 0xa0, v190
	v_ashrrev_i32_e32 v17, 31, v16
	v_lshlrev_b64 v[16:17], 6, v[16:17]
	v_lshl_add_u64 v[16:17], v[202:203], 0, v[16:17]
	global_load_dwordx4 v[128:131], v[16:17], off
	v_or_b32_e32 v16, 0xb0, v190
	v_ashrrev_i32_e32 v17, 31, v16
	v_lshlrev_b64 v[16:17], 6, v[16:17]
	v_lshl_add_u64 v[16:17], v[202:203], 0, v[16:17]
	v_mfma_f32_16x16x32_bf16 v[72:75], v[104:107], v[160:163], v[72:75]
	v_mfma_f32_16x16x32_bf16 v[88:91], v[132:135], v[160:163], v[88:91]
	v_mfma_f32_16x16x32_bf16 v[8:11], v[104:107], v[144:147], v[8:11]
	v_mfma_f32_16x16x32_bf16 v[104:107], v[132:135], v[144:147], v[40:43]
	global_load_dwordx4 v[132:135], v[16:17], off
	v_or_b32_e32 v16, 0xc0, v190
	v_ashrrev_i32_e32 v17, 31, v16
	v_lshlrev_b64 v[16:17], 6, v[16:17]
	v_lshl_add_u64 v[16:17], v[202:203], 0, v[16:17]
	global_load_dwordx4 v[136:139], v[16:17], off
	v_or_b32_e32 v16, 0xd0, v190
	v_ashrrev_i32_e32 v17, 31, v16
	v_lshlrev_b64 v[16:17], 6, v[16:17]
	v_lshl_add_u64 v[16:17], v[202:203], 0, v[16:17]
	global_load_dwordx4 v[144:147], v[16:17], off
	v_or_b32_e32 v16, 0xe0, v190
	v_ashrrev_i32_e32 v17, 31, v16
	v_lshlrev_b64 v[16:17], 6, v[16:17]
	v_lshl_add_u64 v[16:17], v[202:203], 0, v[16:17]
	global_load_dwordx4 v[152:155], v[16:17], off
	v_or_b32_e32 v16, 0xf0, v190
	v_ashrrev_i32_e32 v17, 31, v16
	v_lshlrev_b64 v[16:17], 6, v[16:17]
	v_lshl_add_u64 v[16:17], v[202:203], 0, v[16:17]
	v_mfma_f32_16x16x32_bf16 v[80:83], v[112:115], v[160:163], v[80:83]
	global_load_dwordx4 v[160:163], v[16:17], off
	s_waitcnt vmcnt(15)
	v_mfma_f32_16x16x32_bf16 v[16:19], v[168:171], v[44:47], 0
	v_sub_u32_e32 v36, v191, v239
	v_cvt_f32_ubyte0_e32 v36, v36
	v_mul_f32_e32 v36, v185, v36
	s_waitcnt vmcnt(14)
	v_mfma_f32_16x16x32_bf16 v[16:19], v[172:175], v[48:51], v[16:19]
	v_exp_f32_e32 v36, v36
	v_or_b32_e32 v240, 33, v208
	v_or_b32_e32 v241, 34, v208
	s_waitcnt vmcnt(13)
	v_mfma_f32_16x16x32_bf16 v[16:19], v[176:179], v[52:55], v[16:19]
	v_or_b32_e32 v242, 35, v208
	v_or_b32_e32 v243, 49, v208
	v_or_b32_e32 v244, 50, v208
	s_waitcnt vmcnt(12)
	v_mfma_f32_16x16x32_bf16 v[16:19], v[180:183], v[56:59], v[16:19]
	v_or_b32_e32 v245, 51, v208
	s_mov_b64 s[4:5], 0x10000
	s_nop 5
	v_mul_f32_e32 v16, v36, v16
	v_sub_u32_e32 v36, v191, v240
	v_cvt_f32_ubyte0_e32 v36, v36
	v_mul_f32_e32 v36, v185, v36
	v_exp_f32_e32 v36, v36
	s_nop 0
	v_mul_f32_e32 v17, v36, v17
	v_sub_u32_e32 v36, v191, v241
	v_cvt_f32_ubyte0_e32 v36, v36
	v_mul_f32_e32 v36, v185, v36
	v_exp_f32_e32 v36, v36
	v_cvt_pk_bf16_f32 v116, v16, v17
	s_nop 0
	v_mul_f32_e32 v18, v36, v18
	v_sub_u32_e32 v36, v191, v242
	v_cvt_f32_ubyte0_e32 v36, v36
	v_mul_f32_e32 v36, v185, v36
	v_exp_f32_e32 v36, v36
	s_nop 0
	v_mul_f32_e32 v19, v36, v19
	v_cvt_pk_bf16_f32 v117, v18, v19
	s_waitcnt vmcnt(11)
	v_mfma_f32_16x16x32_bf16 v[16:19], v[164:167], v[44:47], 0
	v_sub_u32_e32 v36, v191, v222
	v_cvt_f32_ubyte0_e32 v36, v36
	v_mul_f32_e32 v36, v185, v36
	s_waitcnt vmcnt(10)
	v_mfma_f32_16x16x32_bf16 v[16:19], v[156:159], v[48:51], v[16:19]
	v_exp_f32_e32 v36, v36
	s_waitcnt vmcnt(9)
	v_mfma_f32_16x16x32_bf16 v[16:19], v[148:151], v[52:55], v[16:19]
	s_waitcnt vmcnt(8)
	v_mfma_f32_16x16x32_bf16 v[16:19], v[140:143], v[56:59], v[16:19]
	s_nop 7
	v_mul_f32_e32 v16, v36, v16
	v_sub_u32_e32 v36, v191, v243
	v_cvt_f32_ubyte0_e32 v36, v36
	v_mul_f32_e32 v36, v185, v36
	v_exp_f32_e32 v36, v36
	s_nop 0
	v_mul_f32_e32 v17, v36, v17
	v_sub_u32_e32 v36, v191, v244
	v_cvt_f32_ubyte0_e32 v36, v36
	v_mul_f32_e32 v36, v185, v36
	v_exp_f32_e32 v36, v36
	v_cvt_pk_bf16_f32 v118, v16, v17
	s_nop 0
	v_mul_f32_e32 v18, v36, v18
	v_sub_u32_e32 v36, v191, v245
	v_cvt_f32_ubyte0_e32 v36, v36
	v_mul_f32_e32 v36, v185, v36
	v_exp_f32_e32 v36, v36
	s_nop 0
	v_mul_f32_e32 v19, v36, v19
	v_cvt_pk_bf16_f32 v119, v18, v19
	s_waitcnt vmcnt(5)
	v_mfma_f32_16x16x32_bf16 v[40:43], v[128:131], v[116:119], v[72:75]
	v_mfma_f32_16x16x32_bf16 v[72:75], v[168:171], v[32:35], 0
	v_mfma_f32_16x16x32_bf16 v[72:75], v[172:175], v[20:23], v[72:75]
	v_mfma_f32_16x16x32_bf16 v[72:75], v[176:179], v[24:27], v[72:75]
	s_waitcnt vmcnt(4)
	v_mfma_f32_16x16x32_bf16 v[60:63], v[132:135], v[116:119], v[76:79]
	s_nop 2
	v_sub_u32_e32 v76, v189, v239
	v_cvt_f32_ubyte0_e32 v76, v76
	v_mul_f32_e32 v76, v185, v76
	v_mfma_f32_16x16x32_bf16 v[72:75], v[180:183], v[28:31], v[72:75]
	v_exp_f32_e32 v76, v76
	v_sub_u32_e32 v78, v189, v222
	v_cvt_f32_ubyte0_e32 v78, v78
	v_mul_f32_e32 v78, v185, v78
	v_exp_f32_e32 v78, v78
	s_nop 2
	v_mul_f32_e32 v72, v76, v72
	v_sub_u32_e32 v76, v189, v240
	v_cvt_f32_ubyte0_e32 v76, v76
	v_mul_f32_e32 v76, v185, v76
	v_exp_f32_e32 v76, v76
	v_mfma_f32_16x16x32_bf16 v[16:19], v[120:123], v[116:119], v[64:67]
	v_mul_f32_e32 v73, v76, v73
	v_sub_u32_e32 v76, v189, v241
	v_cvt_f32_ubyte0_e32 v76, v76
	v_mul_f32_e32 v76, v185, v76
	v_exp_f32_e32 v76, v76
	v_cvt_pk_bf16_f32 v72, v72, v73
	v_mfma_f32_16x16x32_bf16 v[36:39], v[124:127], v[116:119], v[68:71]
	v_mul_f32_e32 v74, v76, v74
	v_sub_u32_e32 v76, v189, v242
	v_cvt_f32_ubyte0_e32 v76, v76
	v_mul_f32_e32 v76, v185, v76
	v_exp_f32_e32 v76, v76
	s_waitcnt vmcnt(3)
	v_mfma_f32_16x16x32_bf16 v[64:67], v[136:139], v[116:119], v[80:83]
	v_mul_f32_e32 v75, v76, v75
	v_cvt_pk_bf16_f32 v73, v74, v75
	v_mfma_f32_16x16x32_bf16 v[74:77], v[164:167], v[32:35], 0
	s_nop 0
	v_mfma_f32_16x16x32_bf16 v[74:77], v[156:159], v[20:23], v[74:77]
	v_mfma_f32_16x16x32_bf16 v[74:77], v[148:151], v[24:27], v[74:77]
	v_mfma_f32_16x16x32_bf16 v[74:77], v[140:143], v[28:31], v[74:77]
	s_waitcnt vmcnt(2)
	v_mfma_f32_16x16x32_bf16 v[68:71], v[144:147], v[116:119], v[84:87]
	s_waitcnt vmcnt(1)
	v_mfma_f32_16x16x32_bf16 v[112:115], v[152:155], v[116:119], v[88:91]
	s_nop 3
	v_mul_f32_e32 v74, v78, v74
	v_sub_u32_e32 v78, v189, v243
	v_cvt_f32_ubyte0_e32 v78, v78
	v_mul_f32_e32 v78, v185, v78
	v_exp_f32_e32 v78, v78
	s_waitcnt vmcnt(0)
	v_mfma_f32_16x16x32_bf16 v[116:119], v[160:163], v[116:119], v[92:95]
	v_mul_f32_e32 v75, v78, v75
	v_sub_u32_e32 v78, v189, v244
	v_cvt_f32_ubyte0_e32 v78, v78
	v_mul_f32_e32 v78, v185, v78
	v_exp_f32_e32 v78, v78
	v_cvt_pk_bf16_f32 v74, v74, v75
	s_nop 0
	v_mul_f32_e32 v76, v78, v76
	v_sub_u32_e32 v78, v189, v245
	v_cvt_f32_ubyte0_e32 v78, v78
	v_mul_f32_e32 v78, v185, v78
	v_exp_f32_e32 v78, v78
	s_nop 0
	v_mul_f32_e32 v77, v78, v77
	v_cvt_pk_bf16_f32 v75, v76, v77
	s_nop 0
	v_mfma_f32_16x16x32_bf16 v[0:3], v[120:123], v[72:75], v[0:3]
	v_mfma_f32_16x16x32_bf16 v[4:7], v[124:127], v[72:75], v[4:7]
	v_mfma_f32_16x16x32_bf16 v[8:11], v[128:131], v[72:75], v[8:11]
	v_mfma_f32_16x16x32_bf16 v[12:15], v[132:135], v[72:75], v[12:15]
	v_mfma_f32_16x16x32_bf16 v[96:99], v[136:139], v[72:75], v[96:99]
	v_mfma_f32_16x16x32_bf16 v[100:103], v[144:147], v[72:75], v[100:103]
	v_mfma_f32_16x16x32_bf16 v[104:107], v[152:155], v[72:75], v[104:107]
	v_mfma_f32_16x16x32_bf16 v[108:111], v[160:163], v[72:75], v[108:111]
	v_add_co_u32_e32 v74, vcc, s72, v204
	v_lshl_add_u64 v[72:73], v[204:205], 0, s[4:5]
	s_nop 0
	v_addc_co_u32_e32 v75, vcc, 0, v205, vcc
	s_mov_b64 s[4:5], 0x14000
	global_load_dwordx4 v[168:171], v[74:75], off
	global_load_dwordx4 v[172:175], v[72:73], off offset:1024
	global_load_dwordx4 v[176:179], v[72:73], off offset:2048
	global_load_dwordx4 v[180:183], v[72:73], off offset:3072
	v_lshl_add_u64 v[72:73], v[204:205], 0, s[4:5]
	s_mov_b32 s4, 0x14000
	v_add_co_u32_e32 v74, vcc, s4, v204
	s_nop 1
	v_addc_co_u32_e32 v75, vcc, 0, v205, vcc
	global_load_dwordx4 v[164:167], v[74:75], off
	global_load_dwordx4 v[152:155], v[72:73], off offset:1024
	global_load_dwordx4 v[156:159], v[72:73], off offset:2048
	global_load_dwordx4 v[160:163], v[72:73], off offset:3072
	v_or_b32_e32 v72, 0x100, v190
	v_ashrrev_i32_e32 v73, 31, v72
	v_lshlrev_b64 v[72:73], 6, v[72:73]
	v_lshl_add_u64 v[72:73], v[202:203], 0, v[72:73]
	global_load_dwordx4 v[120:123], v[72:73], off
	v_or_b32_e32 v72, 0x110, v190
	v_ashrrev_i32_e32 v73, 31, v72
	v_lshlrev_b64 v[72:73], 6, v[72:73]
	v_lshl_add_u64 v[72:73], v[202:203], 0, v[72:73]
	global_load_dwordx4 v[124:127], v[72:73], off
	v_or_b32_e32 v72, 0x120, v190
	v_ashrrev_i32_e32 v73, 31, v72
	v_lshlrev_b64 v[72:73], 6, v[72:73]
	v_lshl_add_u64 v[72:73], v[202:203], 0, v[72:73]
	global_load_dwordx4 v[128:131], v[72:73], off
	v_or_b32_e32 v72, 0x130, v190
	v_ashrrev_i32_e32 v73, 31, v72
	v_lshlrev_b64 v[72:73], 6, v[72:73]
	v_lshl_add_u64 v[72:73], v[202:203], 0, v[72:73]
	global_load_dwordx4 v[132:135], v[72:73], off
	v_or_b32_e32 v72, 0x140, v190
	v_ashrrev_i32_e32 v73, 31, v72
	v_lshlrev_b64 v[72:73], 6, v[72:73]
	v_lshl_add_u64 v[72:73], v[202:203], 0, v[72:73]
	global_load_dwordx4 v[136:139], v[72:73], off
	v_or_b32_e32 v72, 0x150, v190
	v_ashrrev_i32_e32 v73, 31, v72
	v_lshlrev_b64 v[72:73], 6, v[72:73]
	v_lshl_add_u64 v[72:73], v[202:203], 0, v[72:73]
	global_load_dwordx4 v[140:143], v[72:73], off
	v_or_b32_e32 v72, 0x160, v190
	v_ashrrev_i32_e32 v73, 31, v72
	v_lshlrev_b64 v[72:73], 6, v[72:73]
	v_lshl_add_u64 v[72:73], v[202:203], 0, v[72:73]
	global_load_dwordx4 v[144:147], v[72:73], off
	v_or_b32_e32 v72, 0x170, v190
	v_ashrrev_i32_e32 v73, 31, v72
	v_lshlrev_b64 v[72:73], 6, v[72:73]
	v_lshl_add_u64 v[72:73], v[202:203], 0, v[72:73]
	global_load_dwordx4 v[148:151], v[72:73], off
	s_waitcnt vmcnt(15)
	v_mfma_f32_16x16x32_bf16 v[72:75], v[168:171], v[44:47], 0
	v_or_b32_e32 v204, 64, v208
	v_sub_u32_e32 v76, v191, v204
	v_cmp_lt_i32_e32 vcc, -1, v76
	s_waitcnt vmcnt(14)
	v_mfma_f32_16x16x32_bf16 v[72:75], v[172:175], v[48:51], v[72:75]
	v_cvt_f32_u32_e32 v76, v76
	v_or_b32_e32 v205, 0x41, v208
	v_or_b32_e32 v222, 0x42, v208
	s_waitcnt vmcnt(13)
	v_mfma_f32_16x16x32_bf16 v[72:75], v[176:179], v[52:55], v[72:75]
	v_mul_f32_e32 v76, v185, v76
	v_exp_f32_e32 v76, v76
	v_or_b32_e32 v239, 0x43, v208
	s_waitcnt vmcnt(12)
	v_mfma_f32_16x16x32_bf16 v[72:75], v[180:183], v[56:59], v[72:75]
	v_or_b32_e32 v244, 0x51, v208
	v_or_b32_e32 v245, 0x52, v208
	v_or_b32_e32 v246, 0x53, v208
	s_cmp_eq_u32 s70, 0
	s_nop 3
	v_mul_f32_e32 v72, v76, v72
	v_sub_u32_e32 v76, v191, v205
	v_cndmask_b32_e32 v72, 0, v72, vcc
	v_cmp_lt_i32_e32 vcc, -1, v76
	v_cvt_f32_u32_e32 v76, v76
	v_mul_f32_e32 v76, v185, v76
	v_exp_f32_e32 v76, v76
	s_nop 0
	v_mul_f32_e32 v73, v76, v73
	v_sub_u32_e32 v76, v191, v222
	v_cndmask_b32_e32 v73, 0, v73, vcc
	v_cmp_lt_i32_e32 vcc, -1, v76
	v_cvt_f32_u32_e32 v76, v76
	v_cvt_pk_bf16_f32 v240, v72, v73
	v_mul_f32_e32 v76, v185, v76
	v_exp_f32_e32 v76, v76
	s_nop 0
	v_mul_f32_e32 v74, v76, v74
	v_sub_u32_e32 v76, v191, v239
	v_cndmask_b32_e32 v74, 0, v74, vcc
	v_cmp_lt_i32_e32 vcc, -1, v76
	v_cvt_f32_u32_e32 v76, v76
	v_mul_f32_e32 v76, v185, v76
	v_exp_f32_e32 v76, v76
	s_nop 0
	v_mul_f32_e32 v75, v76, v75
	v_cndmask_b32_e32 v75, 0, v75, vcc
	v_cvt_pk_bf16_f32 v241, v74, v75
	s_waitcnt vmcnt(11)
	v_mfma_f32_16x16x32_bf16 v[72:75], v[164:167], v[44:47], 0
	v_or_b32_e32 v76, 0x50, v208
	v_sub_u32_e32 v76, v191, v76
	v_cmp_lt_i32_e32 vcc, -1, v76
	s_waitcnt vmcnt(10)
	v_mfma_f32_16x16x32_bf16 v[72:75], v[152:155], v[48:51], v[72:75]
	v_cvt_f32_u32_e32 v76, v76
	v_mul_f32_e32 v76, v185, v76
	s_waitcnt vmcnt(9)
	v_mfma_f32_16x16x32_bf16 v[72:75], v[156:159], v[52:55], v[72:75]
	v_exp_f32_e32 v76, v76
	s_waitcnt vmcnt(8)
	v_mfma_f32_16x16x32_bf16 v[72:75], v[160:163], v[56:59], v[72:75]
	s_nop 7
	v_mul_f32_e32 v72, v76, v72
	v_sub_u32_e32 v76, v191, v244
	v_cndmask_b32_e32 v72, 0, v72, vcc
	v_cmp_lt_i32_e32 vcc, -1, v76
	v_cvt_f32_u32_e32 v76, v76
	v_mul_f32_e32 v76, v185, v76
	v_exp_f32_e32 v76, v76
	s_nop 0
	v_mul_f32_e32 v73, v76, v73
	v_sub_u32_e32 v76, v191, v245
	v_cndmask_b32_e32 v73, 0, v73, vcc
	v_cmp_lt_i32_e32 vcc, -1, v76
	v_cvt_f32_u32_e32 v76, v76
	v_cvt_pk_bf16_f32 v242, v72, v73
	v_mul_f32_e32 v76, v185, v76
	v_exp_f32_e32 v76, v76
	s_nop 0
	v_mul_f32_e32 v74, v76, v74
	v_sub_u32_e32 v76, v191, v246
	v_cndmask_b32_e32 v74, 0, v74, vcc
	v_cmp_lt_i32_e32 vcc, -1, v76
	v_cvt_f32_u32_e32 v76, v76
	v_mul_f32_e32 v76, v185, v76
	v_exp_f32_e32 v76, v76
	s_nop 0
	v_mul_f32_e32 v75, v76, v75
	v_cndmask_b32_e32 v75, 0, v75, vcc
	v_cvt_pk_bf16_f32 v243, v74, v75
	s_waitcnt vmcnt(7)
	v_mfma_f32_16x16x32_bf16 v[92:95], v[120:123], v[240:243], v[16:19]
	v_mfma_f32_16x16x32_bf16 v[16:19], v[168:171], v[32:35], 0
	v_mfma_f32_16x16x32_bf16 v[16:19], v[172:175], v[20:23], v[16:19]
	v_mfma_f32_16x16x32_bf16 v[16:19], v[176:179], v[24:27], v[16:19]
	s_waitcnt vmcnt(6)
	v_mfma_f32_16x16x32_bf16 v[88:91], v[124:127], v[240:243], v[36:39]
	s_nop 2
	v_sub_u32_e32 v36, v189, v204
	v_cvt_f32_ubyte0_e32 v36, v36
	v_mul_f32_e32 v36, v185, v36
	v_mfma_f32_16x16x32_bf16 v[16:19], v[180:183], v[28:31], v[16:19]
	v_exp_f32_e32 v36, v36
	s_waitcnt vmcnt(2)
	v_mfma_f32_16x16x32_bf16 v[72:75], v[140:143], v[240:243], v[68:71]
	s_waitcnt vmcnt(1)
	v_mfma_f32_16x16x32_bf16 v[68:71], v[144:147], v[240:243], v[112:115]
	s_nop 2
	v_mul_f32_e32 v16, v36, v16
	v_sub_u32_e32 v36, v189, v205
	v_cvt_f32_ubyte0_e32 v36, v36
	v_mul_f32_e32 v36, v185, v36
	v_exp_f32_e32 v36, v36
	v_mfma_f32_16x16x32_bf16 v[84:87], v[128:131], v[240:243], v[40:43]
	v_mul_f32_e32 v17, v36, v17
	v_sub_u32_e32 v36, v189, v222
	v_cvt_f32_ubyte0_e32 v36, v36
	v_mul_f32_e32 v36, v185, v36
	v_exp_f32_e32 v36, v36
	v_cvt_pk_bf16_f32 v112, v16, v17
	v_mfma_f32_16x16x32_bf16 v[80:83], v[132:135], v[240:243], v[60:63]
	v_mul_f32_e32 v18, v36, v18
	v_sub_u32_e32 v36, v189, v239
	v_cvt_f32_ubyte0_e32 v36, v36
	v_mul_f32_e32 v36, v185, v36
	v_exp_f32_e32 v36, v36
	v_mfma_f32_16x16x32_bf16 v[76:79], v[136:139], v[240:243], v[64:67]
	v_mul_f32_e32 v19, v36, v19
	v_cvt_pk_bf16_f32 v113, v18, v19
	v_mfma_f32_16x16x32_bf16 v[16:19], v[164:167], v[32:35], 0
	v_sub_u32_e32 v36, v212, v208
	v_cmp_lt_i32_e32 vcc, -1, v36
	v_cvt_f32_u32_e32 v36, v36
	v_mfma_f32_16x16x32_bf16 v[16:19], v[152:155], v[20:23], v[16:19]
	v_mul_f32_e32 v36, v185, v36
	v_mfma_f32_16x16x32_bf16 v[16:19], v[156:159], v[24:27], v[16:19]
	v_exp_f32_e32 v36, v36
	v_mfma_f32_16x16x32_bf16 v[16:19], v[160:163], v[28:31], v[16:19]
	s_waitcnt vmcnt(0)
	v_mfma_f32_16x16x32_bf16 v[64:67], v[148:151], v[240:243], v[116:119]
	s_nop 5
	v_mul_f32_e32 v16, v36, v16
	v_sub_u32_e32 v36, v189, v244
	v_cndmask_b32_e32 v16, 0, v16, vcc
	v_cmp_lt_i32_e32 vcc, -1, v36
	v_cvt_f32_u32_e32 v36, v36
	v_mul_f32_e32 v36, v185, v36
	v_exp_f32_e32 v36, v36
	s_nop 0
	v_mul_f32_e32 v17, v36, v17
	v_sub_u32_e32 v36, v189, v245
	v_cndmask_b32_e32 v17, 0, v17, vcc
	v_cmp_lt_i32_e32 vcc, -1, v36
	v_cvt_f32_u32_e32 v36, v36
	v_cvt_pk_bf16_f32 v114, v16, v17
	v_mul_f32_e32 v36, v185, v36
	v_exp_f32_e32 v36, v36
	s_nop 0
	v_mul_f32_e32 v18, v36, v18
	v_sub_u32_e32 v36, v189, v246
	v_cndmask_b32_e32 v18, 0, v18, vcc
	v_cmp_lt_i32_e32 vcc, -1, v36
	v_cvt_f32_u32_e32 v36, v36
	v_mul_f32_e32 v36, v185, v36
	v_exp_f32_e32 v36, v36
	s_nop 0
	v_mul_f32_e32 v19, v36, v19
	v_cndmask_b32_e32 v19, 0, v19, vcc
	v_cvt_pk_bf16_f32 v115, v18, v19
	s_nop 0
	v_mfma_f32_16x16x32_bf16 v[60:63], v[120:123], v[112:115], v[0:3]
	v_mfma_f32_16x16x32_bf16 v[40:43], v[124:127], v[112:115], v[4:7]
	v_mfma_f32_16x16x32_bf16 v[36:39], v[128:131], v[112:115], v[8:11]
	v_mfma_f32_16x16x32_bf16 v[16:19], v[132:135], v[112:115], v[12:15]
	v_mfma_f32_16x16x32_bf16 v[12:15], v[136:139], v[112:115], v[96:99]
	v_mfma_f32_16x16x32_bf16 v[8:11], v[140:143], v[112:115], v[100:103]
	v_mfma_f32_16x16x32_bf16 v[4:7], v[144:147], v[112:115], v[104:107]
	v_mfma_f32_16x16x32_bf16 v[0:3], v[148:151], v[112:115], v[108:111]
	s_cbranch_scc1 .LBB0_787
	s_add_u32 s0, s0, s10
	s_addc_u32 s1, s1, s11
	v_lshl_add_u64 v[96:97], s[0:1], 0, v[186:187]
	s_mov_b64 s[0:1], 0x18000
	v_add_co_u32_e32 v100, vcc, 0x18000, v96
	v_lshl_add_u64 v[98:99], v[96:97], 0, s[0:1]
	s_nop 0
	v_addc_co_u32_e32 v101, vcc, 0, v97, vcc
	s_mov_b64 s[0:1], 0x1c000
	global_load_dwordx4 v[144:147], v[98:99], off offset:1024
	global_load_dwordx4 v[148:151], v[98:99], off offset:2048
	global_load_dwordx4 v[156:159], v[100:101], off
	global_load_dwordx4 v[152:155], v[98:99], off offset:3072
	v_lshl_add_u64 v[98:99], v[96:97], 0, s[0:1]
	v_add_co_u32_e32 v96, vcc, 0x1c000, v96
	v_or_b32_e32 v104, 0x1a0, v190
	s_nop 0
	v_addc_co_u32_e32 v97, vcc, 0, v97, vcc
	global_load_dwordx4 v[128:131], v[98:99], off offset:1024
	global_load_dwordx4 v[132:135], v[98:99], off offset:2048
	global_load_dwordx4 v[140:143], v[96:97], off
	global_load_dwordx4 v[136:139], v[98:99], off offset:3072
	v_or_b32_e32 v96, 0x180, v190
	v_or_b32_e32 v98, 0x190, v190
	v_or_b32_e32 v106, 0x1b0, v190
	v_or_b32_e32 v112, 0x1c0, v190
	v_or_b32_e32 v114, 0x1d0, v190
	v_or_b32_e32 v120, 0x1e0, v190
	v_or_b32_e32 v122, 0x1f0, v190
	v_ashrrev_i32_e32 v97, 31, v96
	v_ashrrev_i32_e32 v99, 31, v98
	v_ashrrev_i32_e32 v105, 31, v104
	v_ashrrev_i32_e32 v107, 31, v106
	v_ashrrev_i32_e32 v113, 31, v112
	v_ashrrev_i32_e32 v115, 31, v114
	v_ashrrev_i32_e32 v121, 31, v120
	v_ashrrev_i32_e32 v123, 31, v122
	v_lshlrev_b64 v[96:97], 6, v[96:97]
	v_lshlrev_b64 v[98:99], 6, v[98:99]
	v_lshlrev_b64 v[104:105], 6, v[104:105]
	v_lshlrev_b64 v[106:107], 6, v[106:107]
	v_lshlrev_b64 v[112:113], 6, v[112:113]
	v_lshlrev_b64 v[114:115], 6, v[114:115]
	v_lshlrev_b64 v[120:121], 6, v[120:121]
	v_lshlrev_b64 v[122:123], 6, v[122:123]
	v_lshl_add_u64 v[96:97], v[202:203], 0, v[96:97]
	v_lshl_add_u64 v[100:101], v[202:203], 0, v[98:99]
	v_lshl_add_u64 v[104:105], v[202:203], 0, v[104:105]
	v_lshl_add_u64 v[108:109], v[202:203], 0, v[106:107]
	v_lshl_add_u64 v[112:113], v[202:203], 0, v[112:113]
	v_lshl_add_u64 v[116:117], v[202:203], 0, v[114:115]
	v_lshl_add_u64 v[120:121], v[202:203], 0, v[120:121]
	v_lshl_add_u64 v[124:125], v[202:203], 0, v[122:123]
	global_load_dwordx4 v[96:99], v[96:97], off
	s_nop 0
	global_load_dwordx4 v[100:103], v[100:101], off
	s_nop 0
	global_load_dwordx4 v[104:107], v[104:105], off
	s_nop 0
	global_load_dwordx4 v[108:111], v[108:109], off
	s_nop 0
	global_load_dwordx4 v[112:115], v[112:113], off
	s_nop 0
	global_load_dwordx4 v[116:119], v[116:117], off
	s_nop 0
	global_load_dwordx4 v[120:123], v[120:121], off
	s_nop 0
	global_load_dwordx4 v[124:127], v[124:125], off
	s_waitcnt vmcnt(13)
	v_mfma_f32_16x16x32_bf16 v[44:47], v[156:159], v[44:47], 0
	v_mfma_f32_16x16x32_bf16 v[44:47], v[144:147], v[48:51], v[44:47]
	v_or_b32_e32 v49, 0x61, v208
	v_sub_u32_e32 v50, v238, v49
	v_cmp_lt_i32_e64 s[40:41], -1, v50
	v_cvt_f32_u32_e32 v50, v50
	v_mfma_f32_16x16x32_bf16 v[44:47], v[148:151], v[52:55], v[44:47]
	v_sub_u32_e32 v48, v206, v208
	v_cmp_lt_i32_e32 vcc, -1, v48
	v_mul_f32_e32 v50, v185, v50
	s_waitcnt vmcnt(12)
	v_mfma_f32_16x16x32_bf16 v[44:47], v[152:155], v[56:59], v[44:47]
	v_exp_f32_e32 v50, v50
	v_cvt_f32_u32_e32 v48, v48
	v_sub_u32_e32 v49, v223, v49
	v_cvt_f32_ubyte0_e32 v49, v49
	v_mul_f32_e32 v49, v185, v49
	s_nop 2
	v_mul_f32_e32 v45, v50, v45
	v_or_b32_e32 v50, 0x62, v208
	v_sub_u32_e32 v51, v238, v50
	v_cndmask_b32_e64 v45, 0, v45, s[40:41]
	v_cmp_lt_i32_e64 s[40:41], -1, v51
	v_cvt_f32_u32_e32 v51, v51
	v_mul_f32_e32 v48, v185, v48
	v_exp_f32_e32 v48, v48
	v_exp_f32_e32 v49, v49
	v_mul_f32_e32 v51, v185, v51
	v_exp_f32_e32 v51, v51
	v_mul_f32_e32 v44, v48, v44
	v_cndmask_b32_e32 v44, 0, v44, vcc
	v_cvt_pk_bf16_f32 v44, v44, v45
	v_mul_f32_e32 v46, v51, v46
	v_or_b32_e32 v51, 0x63, v208
	v_sub_u32_e32 v52, v238, v51
	v_cndmask_b32_e64 v46, 0, v46, s[40:41]
	v_cmp_lt_i32_e64 s[40:41], -1, v52
	v_cvt_f32_u32_e32 v52, v52
	v_mul_f32_e32 v52, v185, v52
	v_exp_f32_e32 v52, v52
	s_nop 0
	v_mul_f32_e32 v47, v52, v47
	v_cndmask_b32_e64 v47, 0, v47, s[40:41]
	v_cvt_pk_bf16_f32 v45, v46, v47
	v_cvt_pk_bf16_f32 v46, v197, v197
	v_cvt_pk_bf16_f32 v47, v197, v197
	v_sub_u32_e32 v52, v210, v208
	v_cvt_f32_ubyte0_e32 v52, v52
	s_waitcnt vmcnt(7)
	v_mfma_f32_16x16x32_bf16 v[92:95], v[96:99], v[44:47], v[92:95]
	v_mul_f32_e32 v52, v185, v52
	v_exp_f32_e32 v52, v52
	s_waitcnt vmcnt(6)
	v_mfma_f32_16x16x32_bf16 v[88:91], v[100:103], v[44:47], v[88:91]
	s_waitcnt vmcnt(5)
	v_mfma_f32_16x16x32_bf16 v[84:87], v[104:107], v[44:47], v[84:87]
	s_waitcnt vmcnt(4)
	v_mfma_f32_16x16x32_bf16 v[80:83], v[108:111], v[44:47], v[80:83]
	s_waitcnt vmcnt(3)
	v_mfma_f32_16x16x32_bf16 v[76:79], v[112:115], v[44:47], v[76:79]
	s_waitcnt vmcnt(2)
	v_mfma_f32_16x16x32_bf16 v[72:75], v[116:119], v[44:47], v[72:75]
	s_waitcnt vmcnt(1)
	v_mfma_f32_16x16x32_bf16 v[68:71], v[120:123], v[44:47], v[68:71]
	s_waitcnt vmcnt(0)
	v_mfma_f32_16x16x32_bf16 v[64:67], v[124:127], v[44:47], v[64:67]
	v_mfma_f32_16x16x32_bf16 v[44:47], v[156:159], v[32:35], 0
	v_mfma_f32_16x16x32_bf16 v[32:35], v[140:143], v[32:35], 0
	v_mfma_f32_16x16x32_bf16 v[44:47], v[144:147], v[20:23], v[44:47]
	v_mfma_f32_16x16x32_bf16 v[20:23], v[128:131], v[20:23], v[32:35]
	v_mfma_f32_16x16x32_bf16 v[20:23], v[132:135], v[24:27], v[20:23]
	v_mfma_f32_16x16x32_bf16 v[20:23], v[136:139], v[28:31], v[20:23]
	v_mfma_f32_16x16x32_bf16 v[44:47], v[148:151], v[24:27], v[44:47]
	v_or_b32_e32 v24, 0x71, v208
	s_nop 5
	v_mul_f32_e32 v20, v48, v20
	v_sub_u32_e32 v24, v223, v24
	v_cndmask_b32_e32 v20, 0, v20, vcc
	v_cmp_lt_i32_e32 vcc, -1, v24
	v_cvt_f32_u32_e32 v24, v24
	v_mfma_f32_16x16x32_bf16 v[44:47], v[152:155], v[28:31], v[44:47]
	v_mul_f32_e32 v24, v185, v24
	v_exp_f32_e32 v24, v24
	s_nop 0
	v_mul_f32_e32 v21, v24, v21
	v_or_b32_e32 v24, 0x72, v208
	v_sub_u32_e32 v24, v223, v24
	v_cndmask_b32_e32 v21, 0, v21, vcc
	v_cmp_lt_i32_e32 vcc, -1, v24
	v_cvt_f32_u32_e32 v24, v24
	v_mul_f32_e32 v45, v49, v45
	v_sub_u32_e32 v49, v223, v50
	v_cvt_f32_ubyte0_e32 v49, v49
	v_mul_f32_e32 v24, v185, v24
	v_exp_f32_e32 v24, v24
	v_mul_f32_e32 v49, v185, v49
	v_exp_f32_e32 v49, v49
	v_mul_f32_e32 v44, v52, v44
	v_mul_f32_e32 v22, v24, v22
	v_or_b32_e32 v24, 0x73, v208
	v_sub_u32_e32 v24, v223, v24
	v_cndmask_b32_e32 v22, 0, v22, vcc
	v_cmp_lt_i32_e32 vcc, -1, v24
	v_cvt_f32_u32_e32 v24, v24
	v_mul_f32_e32 v46, v49, v46
	v_sub_u32_e32 v49, v223, v51
	v_cvt_f32_ubyte0_e32 v49, v49
	v_mul_f32_e32 v49, v185, v49
	v_mul_f32_e32 v24, v185, v24
	v_exp_f32_e32 v49, v49
	v_exp_f32_e32 v24, v24
	v_cvt_pk_bf16_f32 v44, v44, v45
	v_mul_f32_e32 v47, v49, v47
	v_mul_f32_e32 v23, v24, v23
	v_cvt_pk_bf16_f32 v45, v46, v47
	v_cndmask_b32_e32 v23, 0, v23, vcc
	v_cvt_pk_bf16_f32 v46, v20, v21
	v_cvt_pk_bf16_f32 v47, v22, v23
	s_nop 0
	v_mfma_f32_16x16x32_bf16 v[60:63], v[96:99], v[44:47], v[60:63]
	v_mfma_f32_16x16x32_bf16 v[40:43], v[100:103], v[44:47], v[40:43]
	v_mfma_f32_16x16x32_bf16 v[36:39], v[104:107], v[44:47], v[36:39]
	v_mfma_f32_16x16x32_bf16 v[16:19], v[108:111], v[44:47], v[16:19]
	v_mfma_f32_16x16x32_bf16 v[12:15], v[112:115], v[44:47], v[12:15]
	v_mfma_f32_16x16x32_bf16 v[8:11], v[116:119], v[44:47], v[8:11]
	v_mfma_f32_16x16x32_bf16 v[4:7], v[120:123], v[44:47], v[4:7]
	v_mfma_f32_16x16x32_bf16 v[0:3], v[124:127], v[44:47], v[0:3]
